# v28 + P9 body software-pipelined: S1(mm+1)/S3(mm-1) MFMAs and LDS reads interleaved into the recurrence
# speedup vs baseline: 1.0008x; 1.0008x over previous
; __device__ __forceinline__ void s5_out_phase(LAS unsigned char* lds, const bf16_t* UZ, const unsigned char* ws, const float* dskip, bf16_t* YG) {
;     ...
;         f32x4 accY[4];
; #pragma unroll
;         for (int m = 0; m < 4; ++m) accY[m] = (f32x4){0.f, 0.f, 0.f, 0.f};
; #pragma unroll
;         for (int mm = 0; mm < 4; ++mm) {
;             const int mf = mm, mb = 3 - mm;
; #pragma unroll
;             for (int nt = 0; nt < 8; ++nt) {
;                 const f32x4 z = {0.f, 0.f, 0.f, 0.f};
;                 const f32x4 cf = __builtin_amdgcn_mfma_f32_16x16x16bf16_1k(Uf[mf], Bf[0][nt], z, 0, 0, 0);
;                 const f32x4 cb = __builtin_amdgcn_mfma_f32_16x16x16bf16_1k(Uf[mb], Bf[1][nt], z, 0, 0, 0);
;                 u32x2 wf, wb; wf.x = pk2(cf[0], cf[1]); wf.y = pk2(cf[2], cf[3]); wb.x = pk2(cb[0], cb[1]); wb.y = pk2(cb[2], cb[3]);
;                 *(LAS u32x2*)(wl + nt * 640 + wofs) = wf;
;                 *(LAS u32x2*)(wl + BUT_BYTES + nt * 640 + wofs) = wb;
;             }
;             WAVE_LDS_FENCE();
;             const LAS unsigned char* rp = wl + lane * 80;
;             const u32x4 fre0 = *(const LAS u32x4*)(rp), fre1 = *(const LAS u32x4*)(rp + 16), fim0 = *(const LAS u32x4*)(rp + 32), fim1 = *(const LAS u32x4*)(rp + 48);
;             const u32x4 bre0 = *(const LAS u32x4*)(rp + BUT_BYTES), bre1 = *(const LAS u32x4*)(rp + BUT_BYTES + 16), bim0 = *(const LAS u32x4*)(rp + BUT_BYTES + 32), bim1 = *(const LAS u32x4*)(rp + BUT_BYTES + 48);
;             LAS unsigned char* xf = wl + 2 * BUT_BYTES; LAS unsigned char* xbk = xf + XB_BYTES;
; #pragma unroll
;             for (int rr = 0; rr < 16; ++rr) {
;                 const int r = rr, rb = 15 - rr;
;                 { const f32x2 bb = {bf_at(fre0, fre1, r), bf_at(fim0, fim1, r)};
;                   const f32x2 n2 = cmac((f32x2){xfr, xfi}, (f32x2){ap[0].x, ap[0].x}, (f32x2){-ap[0].y, ap[0].y}, bb); xfr = n2.x; xfi = n2.y;
;                   *(LAS unsigned*)(xf + r * XB_PITCH + lane * 4) = pk2(n2.x, n2.y); }
;                 { const f32x2 bb = {bf_at(bre0, bre1, rb), bf_at(bim0, bim1, rb)};
;                   const f32x2 n2 = cmac((f32x2){xbr, xbi}, (f32x2){ap[1].x, ap[1].x}, (f32x2){-ap[1].y, ap[1].y}, bb); xbr = n2.x; xbi = n2.y;
;                   *(LAS unsigned*)(xbk + rb * XB_PITCH + lane * 4) = pk2(n2.x, n2.y); }
;             }
;             WAVE_LDS_FENCE();
.LBB0_755:
	v_mov_b64_e32 v[194:195], v[44:45]
	v_mov_b64_e32 v[196:197], v[46:47]
	v_mfma_f32_16x16x16_bf16 v[238:241], v[172:173], v[60:61], 0
	v_mfma_f32_16x16x16_bf16 v[242:245], v[116:117], v[76:77], 0
	v_mfma_f32_16x16x16_bf16 v[246:249], v[172:173], v[62:63], 0
	s_nop 5
	v_cvt_pk_bf16_f32 v238, v238, v239
	s_nop 3
	v_cvt_pk_bf16_f32 v239, v240, v241
	ds_write_b64 v104, v[238:239]
	v_mfma_f32_16x16x16_bf16 v[250:253], v[116:117], v[78:79], 0
	s_nop 0
	v_cvt_pk_bf16_f32 v242, v242, v243
	v_cvt_pk_bf16_f32 v243, v244, v245
	ds_write_b64 v104, v[242:243] offset:5120
	v_mfma_f32_16x16x16_bf16 v[238:241], v[172:173], v[64:65], 0
	v_cvt_pk_bf16_f32 v246, v246, v247
	v_cvt_pk_bf16_f32 v247, v248, v249
	ds_write_b64 v104, v[246:247] offset:640
	v_mfma_f32_16x16x16_bf16 v[242:245], v[116:117], v[80:81], 0
	v_cvt_pk_bf16_f32 v250, v250, v251
	v_cvt_pk_bf16_f32 v251, v252, v253
	ds_write_b64 v104, v[250:251] offset:5760
	v_mfma_f32_16x16x16_bf16 v[246:249], v[172:173], v[66:67], 0
	v_cvt_pk_bf16_f32 v238, v238, v239
	v_cvt_pk_bf16_f32 v239, v240, v241
	ds_write_b64 v104, v[238:239] offset:1280
	v_mfma_f32_16x16x16_bf16 v[250:253], v[116:117], v[82:83], 0
	v_cvt_pk_bf16_f32 v242, v242, v243
	v_cvt_pk_bf16_f32 v243, v244, v245
	ds_write_b64 v104, v[242:243] offset:6400
	v_mfma_f32_16x16x16_bf16 v[238:241], v[172:173], v[68:69], 0
	v_cvt_pk_bf16_f32 v246, v246, v247
	v_cvt_pk_bf16_f32 v247, v248, v249
	ds_write_b64 v104, v[246:247] offset:1920
	v_mfma_f32_16x16x16_bf16 v[242:245], v[116:117], v[84:85], 0
	v_cvt_pk_bf16_f32 v250, v250, v251
	v_cvt_pk_bf16_f32 v251, v252, v253
	ds_write_b64 v104, v[250:251] offset:7040
	v_mfma_f32_16x16x16_bf16 v[246:249], v[172:173], v[70:71], 0
	v_cvt_pk_bf16_f32 v238, v238, v239
	v_cvt_pk_bf16_f32 v239, v240, v241
	ds_write_b64 v104, v[238:239] offset:2560
	v_mfma_f32_16x16x16_bf16 v[250:253], v[116:117], v[86:87], 0
	v_cvt_pk_bf16_f32 v242, v242, v243
	v_cvt_pk_bf16_f32 v243, v244, v245
	ds_write_b64 v104, v[242:243] offset:7680
	v_mfma_f32_16x16x16_bf16 v[238:241], v[172:173], v[72:73], 0
	v_cvt_pk_bf16_f32 v246, v246, v247
	v_cvt_pk_bf16_f32 v247, v248, v249
	ds_write_b64 v104, v[246:247] offset:3200
	v_mfma_f32_16x16x16_bf16 v[242:245], v[116:117], v[88:89], 0
	v_cvt_pk_bf16_f32 v250, v250, v251
	v_cvt_pk_bf16_f32 v251, v252, v253
	ds_write_b64 v104, v[250:251] offset:8320
	v_mfma_f32_16x16x16_bf16 v[246:249], v[172:173], v[74:75], 0
	v_cvt_pk_bf16_f32 v238, v238, v239
	v_cvt_pk_bf16_f32 v239, v240, v241
	ds_write_b64 v104, v[238:239] offset:3840
	v_mfma_f32_16x16x16_bf16 v[250:253], v[116:117], v[90:91], 0
	v_cvt_pk_bf16_f32 v242, v242, v243
	v_cvt_pk_bf16_f32 v243, v244, v245
	ds_write_b64 v104, v[242:243] offset:8960
	s_nop 0
	v_cvt_pk_bf16_f32 v246, v246, v247
	v_cvt_pk_bf16_f32 v247, v248, v249
	ds_write_b64 v104, v[246:247] offset:4480
	s_nop 0
	v_cvt_pk_bf16_f32 v250, v250, v251
	v_cvt_pk_bf16_f32 v251, v252, v253
	ds_write_b64 v104, v[250:251] offset:9600
	ds_read_b128 v[206:209], v109
	ds_read_b128 v[210:213], v109 offset:32
	ds_read_b128 v[214:217], v109 offset:5136
	ds_read_b128 v[218:221], v109 offset:5168
	ds_read_b128 v[222:225], v109 offset:16
	ds_read_b128 v[226:229], v109 offset:48
	ds_read_b128 v[230:233], v109 offset:5120
	ds_read_b128 v[234:237], v109 offset:5152
	s_waitcnt lgkmcnt(7)
	v_lshlrev_b32_e32 v198, 16, v206
	s_waitcnt lgkmcnt(6)
	v_lshlrev_b32_e32 v199, 16, v210
	s_waitcnt lgkmcnt(5)
	v_and_b32_e32 v200, 0xffff0000, v217
	s_waitcnt lgkmcnt(4)
	v_and_b32_e32 v201, 0xffff0000, v221
	v_pk_fma_f32 v[198:199], v[150:151], v[194:195], v[198:199]
	v_pk_fma_f32 v[200:201], v[152:153], v[196:197], v[200:201]
	v_and_b32_e32 v202, 0xffff0000, v206
	v_pk_fma_f32 v[194:195], v[16:17], v[194:195], v[198:199] op_sel:[0,1,0] op_sel_hi:[1,0,1]
	v_pk_fma_f32 v[196:197], v[36:37], v[196:197], v[200:201] op_sel:[0,1,0] op_sel_hi:[1,0,1]
	v_mfma_f32_16x16x16_bf16 v[238:241], v[170:171], v[60:61], 0
	v_and_b32_e32 v203, 0xffff0000, v210
	v_cvt_pk_bf16_f32 v114, v194, v195
	v_cvt_pk_bf16_f32 v128, v196, v197
	v_mfma_f32_16x16x16_bf16 v[242:245], v[168:169], v[76:77], 0
	v_lshlrev_b32_e32 v204, 16, v217
	ds_write_b32 v103, v114 offset:10240
	v_lshlrev_b32_e32 v205, 16, v221
	ds_write_b32 v103, v128 offset:18672
	v_cvt_pk_bf16_f32 v238, v238, v239
	v_cvt_pk_bf16_f32 v239, v240, v241
	ds_write_b64 v104, v[238:239]
	v_mfma_f32_16x16x16_bf16 v[246:249], v[170:171], v[62:63], 0
	v_pk_fma_f32 v[202:203], v[150:151], v[194:195], v[202:203]
	v_pk_fma_f32 v[204:205], v[152:153], v[196:197], v[204:205]
	v_lshlrev_b32_e32 v198, 16, v207
	v_pk_fma_f32 v[194:195], v[16:17], v[194:195], v[202:203] op_sel:[0,1,0] op_sel_hi:[1,0,1]
	v_pk_fma_f32 v[196:197], v[36:37], v[196:197], v[204:205] op_sel:[0,1,0] op_sel_hi:[1,0,1]
	v_cvt_pk_bf16_f32 v242, v242, v243
	v_cvt_pk_bf16_f32 v243, v244, v245
	ds_write_b64 v104, v[242:243] offset:5120
	v_mfma_f32_16x16x16_bf16 v[250:253], v[168:169], v[78:79], 0
	v_lshlrev_b32_e32 v199, 16, v211
	v_cvt_pk_bf16_f32 v119, v194, v195
	v_cvt_pk_bf16_f32 v131, v196, v197
	v_cvt_pk_bf16_f32 v246, v246, v247
	v_cvt_pk_bf16_f32 v247, v248, v249
	ds_write_b64 v104, v[246:247] offset:640
	v_mfma_f32_16x16x16_bf16 v[238:241], v[170:171], v[64:65], 0
	v_and_b32_e32 v200, 0xffff0000, v216
	ds_write_b32 v103, v119 offset:10512
	v_and_b32_e32 v201, 0xffff0000, v220
	ds_write_b32 v103, v131 offset:18400
	v_cvt_pk_bf16_f32 v250, v250, v251
	v_cvt_pk_bf16_f32 v251, v252, v253
	ds_write_b64 v104, v[250:251] offset:5760
	v_mfma_f32_16x16x16_bf16 v[242:245], v[168:169], v[80:81], 0
	v_pk_fma_f32 v[198:199], v[150:151], v[194:195], v[198:199]
	v_pk_fma_f32 v[200:201], v[152:153], v[196:197], v[200:201]
; #define LAS __attribute__((address_space(3)))
; #define WAVE_LDS_FENCE() asm volatile("s_waitcnt lgkmcnt(0)" ::: "memory")
; __device__ __forceinline__ void s5_out_phase(LAS unsigned char* lds, const bf16_t* UZ, const unsigned char* ws, const float* dskip, bf16_t* YG) {
;     ...
; #pragma unroll
;         for (int mm = 0; mm < 4; ++mm) {
;             const int mf = mm, mb = 3 - mm;
; #pragma unroll
;             for (int nt = 0; nt < 8; ++nt) {
;                 const f32x4 z = {0.f, 0.f, 0.f, 0.f};
;                 const f32x4 cf = __builtin_amdgcn_mfma_f32_16x16x16bf16_1k(Uf[mf], Bf[0][nt], z, 0, 0, 0);
;                 const f32x4 cb = __builtin_amdgcn_mfma_f32_16x16x16bf16_1k(Uf[mb], Bf[1][nt], z, 0, 0, 0);
;                 u32x2 wf, wb; wf.x = pk2(cf[0], cf[1]); wf.y = pk2(cf[2], cf[3]); wb.x = pk2(cb[0], cb[1]); wb.y = pk2(cb[2], cb[3]);
;                 *(LAS u32x2*)(wl + nt * 640 + wofs) = wf;
;                 *(LAS u32x2*)(wl + BUT_BYTES + nt * 640 + wofs) = wb;
;             }
;             WAVE_LDS_FENCE();
;             const LAS unsigned char* rp = wl + lane * 80;
;             const u32x4 fre0 = *(const LAS u32x4*)(rp), fre1 = *(const LAS u32x4*)(rp + 16), fim0 = *(const LAS u32x4*)(rp + 32), fim1 = *(const LAS u32x4*)(rp + 48);
;             const u32x4 bre0 = *(const LAS u32x4*)(rp + BUT_BYTES), bre1 = *(const LAS u32x4*)(rp + BUT_BYTES + 16), bim0 = *(const LAS u32x4*)(rp + BUT_BYTES + 32), bim1 = *(const LAS u32x4*)(rp + BUT_BYTES + 48);
;             LAS unsigned char* xf = wl + 2 * BUT_BYTES; LAS unsigned char* xbk = xf + XB_BYTES;
; #pragma unroll
;             for (int rr = 0; rr < 16; ++rr) {
;                 const int r = rr, rb = 15 - rr;
;                 { const f32x2 bb = {bf_at(fre0, fre1, r), bf_at(fim0, fim1, r)};
;                   const f32x2 n2 = cmac((f32x2){xfr, xfi}, (f32x2){ap[0].x, ap[0].x}, (f32x2){-ap[0].y, ap[0].y}, bb); xfr = n2.x; xfi = n2.y;
;                   *(LAS unsigned*)(xf + r * XB_PITCH + lane * 4) = pk2(n2.x, n2.y); }
;                 { const f32x2 bb = {bf_at(bre0, bre1, rb), bf_at(bim0, bim1, rb)};
;                   const f32x2 n2 = cmac((f32x2){xbr, xbi}, (f32x2){ap[1].x, ap[1].x}, (f32x2){-ap[1].y, ap[1].y}, bb); xbr = n2.x; xbi = n2.y;
;                   *(LAS unsigned*)(xbk + rb * XB_PITCH + lane * 4) = pk2(n2.x, n2.y); }
;             }
;             WAVE_LDS_FENCE();
	v_and_b32_e32 v202, 0xffff0000, v207
	v_pk_fma_f32 v[194:195], v[16:17], v[194:195], v[198:199] op_sel:[0,1,0] op_sel_hi:[1,0,1]
	v_pk_fma_f32 v[196:197], v[36:37], v[196:197], v[200:201] op_sel:[0,1,0] op_sel_hi:[1,0,1]
	v_cvt_pk_bf16_f32 v238, v238, v239
	v_cvt_pk_bf16_f32 v239, v240, v241
	ds_write_b64 v104, v[238:239] offset:1280
	v_mfma_f32_16x16x16_bf16 v[246:249], v[170:171], v[66:67], 0
	v_and_b32_e32 v203, 0xffff0000, v211
	v_cvt_pk_bf16_f32 v121, v194, v195
	v_cvt_pk_bf16_f32 v132, v196, v197
	v_cvt_pk_bf16_f32 v242, v242, v243
	v_cvt_pk_bf16_f32 v243, v244, v245
	ds_write_b64 v104, v[242:243] offset:6400
	v_mfma_f32_16x16x16_bf16 v[250:253], v[168:169], v[82:83], 0
	v_lshlrev_b32_e32 v204, 16, v216
	ds_write_b32 v103, v121 offset:10784
	v_lshlrev_b32_e32 v205, 16, v220
	ds_write_b32 v103, v132 offset:18128
	v_cvt_pk_bf16_f32 v246, v246, v247
	v_cvt_pk_bf16_f32 v247, v248, v249
	ds_write_b64 v104, v[246:247] offset:1920
	v_mfma_f32_16x16x16_bf16 v[238:241], v[170:171], v[68:69], 0
	v_pk_fma_f32 v[202:203], v[150:151], v[194:195], v[202:203]
	v_pk_fma_f32 v[204:205], v[152:153], v[196:197], v[204:205]
	v_lshlrev_b32_e32 v198, 16, v208
	v_pk_fma_f32 v[194:195], v[16:17], v[194:195], v[202:203] op_sel:[0,1,0] op_sel_hi:[1,0,1]
	v_pk_fma_f32 v[196:197], v[36:37], v[196:197], v[204:205] op_sel:[0,1,0] op_sel_hi:[1,0,1]
	v_cvt_pk_bf16_f32 v250, v250, v251
	v_cvt_pk_bf16_f32 v251, v252, v253
	ds_write_b64 v104, v[250:251] offset:7040
	v_mfma_f32_16x16x16_bf16 v[242:245], v[168:169], v[84:85], 0
	v_lshlrev_b32_e32 v199, 16, v212
	v_cvt_pk_bf16_f32 v127, v194, v195
	v_cvt_pk_bf16_f32 v135, v196, v197
	v_cvt_pk_bf16_f32 v238, v238, v239
	v_cvt_pk_bf16_f32 v239, v240, v241
	ds_write_b64 v104, v[238:239] offset:2560
	v_mfma_f32_16x16x16_bf16 v[246:249], v[170:171], v[70:71], 0
	v_and_b32_e32 v200, 0xffff0000, v215
	ds_write_b32 v103, v127 offset:11056
	v_and_b32_e32 v201, 0xffff0000, v219
	ds_write_b32 v103, v135 offset:17856
	v_cvt_pk_bf16_f32 v242, v242, v243
	v_cvt_pk_bf16_f32 v243, v244, v245
	ds_write_b64 v104, v[242:243] offset:7680
	v_mfma_f32_16x16x16_bf16 v[250:253], v[168:169], v[86:87], 0
	v_pk_fma_f32 v[198:199], v[150:151], v[194:195], v[198:199]
	v_pk_fma_f32 v[200:201], v[152:153], v[196:197], v[200:201]
	v_and_b32_e32 v202, 0xffff0000, v208
	v_pk_fma_f32 v[194:195], v[16:17], v[194:195], v[198:199] op_sel:[0,1,0] op_sel_hi:[1,0,1]
	v_pk_fma_f32 v[196:197], v[36:37], v[196:197], v[200:201] op_sel:[0,1,0] op_sel_hi:[1,0,1]
	v_cvt_pk_bf16_f32 v246, v246, v247
	v_cvt_pk_bf16_f32 v247, v248, v249
	ds_write_b64 v104, v[246:247] offset:3200
	v_mfma_f32_16x16x16_bf16 v[238:241], v[170:171], v[72:73], 0
	v_and_b32_e32 v203, 0xffff0000, v212
	v_cvt_pk_bf16_f32 v114, v194, v195
	v_cvt_pk_bf16_f32 v128, v196, v197
	v_cvt_pk_bf16_f32 v250, v250, v251
	v_cvt_pk_bf16_f32 v251, v252, v253
	ds_write_b64 v104, v[250:251] offset:8320
	v_mfma_f32_16x16x16_bf16 v[242:245], v[168:169], v[88:89], 0
	v_lshlrev_b32_e32 v204, 16, v215
	ds_write_b32 v103, v114 offset:11328
	v_lshlrev_b32_e32 v205, 16, v219
	ds_write_b32 v103, v128 offset:17584
	v_cvt_pk_bf16_f32 v238, v238, v239
	v_cvt_pk_bf16_f32 v239, v240, v241
	ds_write_b64 v104, v[238:239] offset:3840
	v_mfma_f32_16x16x16_bf16 v[246:249], v[170:171], v[74:75], 0
	v_pk_fma_f32 v[202:203], v[150:151], v[194:195], v[202:203]
	v_pk_fma_f32 v[204:205], v[152:153], v[196:197], v[204:205]
	v_lshlrev_b32_e32 v198, 16, v209
	v_pk_fma_f32 v[194:195], v[16:17], v[194:195], v[202:203] op_sel:[0,1,0] op_sel_hi:[1,0,1]
	v_pk_fma_f32 v[196:197], v[36:37], v[196:197], v[204:205] op_sel:[0,1,0] op_sel_hi:[1,0,1]
	v_cvt_pk_bf16_f32 v242, v242, v243
	v_cvt_pk_bf16_f32 v243, v244, v245
	ds_write_b64 v104, v[242:243] offset:8960
	v_mfma_f32_16x16x16_bf16 v[250:253], v[168:169], v[90:91], 0
	v_lshlrev_b32_e32 v199, 16, v213
	v_cvt_pk_bf16_f32 v119, v194, v195
	v_cvt_pk_bf16_f32 v131, v196, v197
	v_cvt_pk_bf16_f32 v246, v246, v247
	v_cvt_pk_bf16_f32 v247, v248, v249
	ds_write_b64 v104, v[246:247] offset:4480
	v_and_b32_e32 v200, 0xffff0000, v214
	ds_write_b32 v103, v119 offset:11600
	v_and_b32_e32 v201, 0xffff0000, v218
	ds_write_b32 v103, v131 offset:17312
	v_cvt_pk_bf16_f32 v250, v250, v251
	v_cvt_pk_bf16_f32 v251, v252, v253
	ds_write_b64 v104, v[250:251] offset:9600
	v_pk_fma_f32 v[198:199], v[150:151], v[194:195], v[198:199]
	v_pk_fma_f32 v[200:201], v[152:153], v[196:197], v[200:201]
	v_and_b32_e32 v202, 0xffff0000, v209
	v_pk_fma_f32 v[194:195], v[16:17], v[194:195], v[198:199] op_sel:[0,1,0] op_sel_hi:[1,0,1]
	v_pk_fma_f32 v[196:197], v[36:37], v[196:197], v[200:201] op_sel:[0,1,0] op_sel_hi:[1,0,1]
	v_and_b32_e32 v203, 0xffff0000, v213
	v_cvt_pk_bf16_f32 v121, v194, v195
	v_cvt_pk_bf16_f32 v132, v196, v197
	v_lshlrev_b32_e32 v204, 16, v214
	ds_write_b32 v103, v121 offset:11872
	v_lshlrev_b32_e32 v205, 16, v218
	ds_write_b32 v103, v132 offset:17040
	v_pk_fma_f32 v[202:203], v[150:151], v[194:195], v[202:203]
	v_pk_fma_f32 v[204:205], v[152:153], v[196:197], v[204:205]
	s_waitcnt lgkmcnt(15)
; #define LAS __attribute__((address_space(3)))
; #define WAVE_LDS_FENCE() asm volatile("s_waitcnt lgkmcnt(0)" ::: "memory")
; __device__ __forceinline__ void s5_out_phase(LAS unsigned char* lds, const bf16_t* UZ, const unsigned char* ws, const float* dskip, bf16_t* YG) {
;     ...
; #pragma unroll
;         for (int mm = 0; mm < 4; ++mm) {
;             const int mf = mm, mb = 3 - mm;
; #pragma unroll
;             for (int nt = 0; nt < 8; ++nt) {
;                 const f32x4 z = {0.f, 0.f, 0.f, 0.f};
;                 const f32x4 cf = __builtin_amdgcn_mfma_f32_16x16x16bf16_1k(Uf[mf], Bf[0][nt], z, 0, 0, 0);
;                 const f32x4 cb = __builtin_amdgcn_mfma_f32_16x16x16bf16_1k(Uf[mb], Bf[1][nt], z, 0, 0, 0);
;                 u32x2 wf, wb; wf.x = pk2(cf[0], cf[1]); wf.y = pk2(cf[2], cf[3]); wb.x = pk2(cb[0], cb[1]); wb.y = pk2(cb[2], cb[3]);
;                 *(LAS u32x2*)(wl + nt * 640 + wofs) = wf;
;                 *(LAS u32x2*)(wl + BUT_BYTES + nt * 640 + wofs) = wb;
;             }
;             WAVE_LDS_FENCE();
;             const LAS unsigned char* rp = wl + lane * 80;
;             const u32x4 fre0 = *(const LAS u32x4*)(rp), fre1 = *(const LAS u32x4*)(rp + 16), fim0 = *(const LAS u32x4*)(rp + 32), fim1 = *(const LAS u32x4*)(rp + 48);
;             const u32x4 bre0 = *(const LAS u32x4*)(rp + BUT_BYTES), bre1 = *(const LAS u32x4*)(rp + BUT_BYTES + 16), bim0 = *(const LAS u32x4*)(rp + BUT_BYTES + 32), bim1 = *(const LAS u32x4*)(rp + BUT_BYTES + 48);
;             LAS unsigned char* xf = wl + 2 * BUT_BYTES; LAS unsigned char* xbk = xf + XB_BYTES;
; #pragma unroll
;             for (int rr = 0; rr < 16; ++rr) {
;                 const int r = rr, rb = 15 - rr;
;                 { const f32x2 bb = {bf_at(fre0, fre1, r), bf_at(fim0, fim1, r)};
;                   const f32x2 n2 = cmac((f32x2){xfr, xfi}, (f32x2){ap[0].x, ap[0].x}, (f32x2){-ap[0].y, ap[0].y}, bb); xfr = n2.x; xfi = n2.y;
;                   *(LAS unsigned*)(xf + r * XB_PITCH + lane * 4) = pk2(n2.x, n2.y); }
;                 { const f32x2 bb = {bf_at(bre0, bre1, rb), bf_at(bim0, bim1, rb)};
;                   const f32x2 n2 = cmac((f32x2){xbr, xbi}, (f32x2){ap[1].x, ap[1].x}, (f32x2){-ap[1].y, ap[1].y}, bb); xbr = n2.x; xbi = n2.y;
;                   *(LAS unsigned*)(xbk + rb * XB_PITCH + lane * 4) = pk2(n2.x, n2.y); }
;             }
;             WAVE_LDS_FENCE();
	v_lshlrev_b32_e32 v198, 16, v222
	v_pk_fma_f32 v[194:195], v[16:17], v[194:195], v[202:203] op_sel:[0,1,0] op_sel_hi:[1,0,1]
	v_pk_fma_f32 v[196:197], v[36:37], v[196:197], v[204:205] op_sel:[0,1,0] op_sel_hi:[1,0,1]
	ds_read_b128 v[206:209], v109
	ds_read_b128 v[210:213], v109 offset:32
	ds_read_b128 v[214:217], v109 offset:5136
	ds_read_b128 v[218:221], v109 offset:5168
	v_lshlrev_b32_e32 v199, 16, v226
	v_cvt_pk_bf16_f32 v127, v194, v195
	v_cvt_pk_bf16_f32 v135, v196, v197
	v_and_b32_e32 v200, 0xffff0000, v233
	ds_write_b32 v103, v127 offset:12144
	v_and_b32_e32 v201, 0xffff0000, v237
	ds_write_b32 v103, v135 offset:16768
	v_pk_fma_f32 v[198:199], v[150:151], v[194:195], v[198:199]
	v_pk_fma_f32 v[200:201], v[152:153], v[196:197], v[200:201]
	v_and_b32_e32 v202, 0xffff0000, v222
	v_pk_fma_f32 v[194:195], v[16:17], v[194:195], v[198:199] op_sel:[0,1,0] op_sel_hi:[1,0,1]
	v_pk_fma_f32 v[196:197], v[36:37], v[196:197], v[200:201] op_sel:[0,1,0] op_sel_hi:[1,0,1]
	v_and_b32_e32 v203, 0xffff0000, v226
	v_cvt_pk_bf16_f32 v114, v194, v195
	v_cvt_pk_bf16_f32 v128, v196, v197
	v_lshlrev_b32_e32 v204, 16, v233
	ds_write_b32 v103, v114 offset:12416
	v_lshlrev_b32_e32 v205, 16, v237
	ds_write_b32 v103, v128 offset:16496
	v_pk_fma_f32 v[202:203], v[150:151], v[194:195], v[202:203]
	v_pk_fma_f32 v[204:205], v[152:153], v[196:197], v[204:205]
	v_lshlrev_b32_e32 v198, 16, v223
	v_pk_fma_f32 v[194:195], v[16:17], v[194:195], v[202:203] op_sel:[0,1,0] op_sel_hi:[1,0,1]
	v_pk_fma_f32 v[196:197], v[36:37], v[196:197], v[204:205] op_sel:[0,1,0] op_sel_hi:[1,0,1]
	v_lshlrev_b32_e32 v199, 16, v227
	v_cvt_pk_bf16_f32 v119, v194, v195
	v_cvt_pk_bf16_f32 v131, v196, v197
	v_and_b32_e32 v200, 0xffff0000, v232
	ds_write_b32 v103, v119 offset:12688
	v_and_b32_e32 v201, 0xffff0000, v236
	ds_write_b32 v103, v131 offset:16224
	v_pk_fma_f32 v[198:199], v[150:151], v[194:195], v[198:199]
	v_pk_fma_f32 v[200:201], v[152:153], v[196:197], v[200:201]
	v_and_b32_e32 v202, 0xffff0000, v223
	v_pk_fma_f32 v[194:195], v[16:17], v[194:195], v[198:199] op_sel:[0,1,0] op_sel_hi:[1,0,1]
	v_pk_fma_f32 v[196:197], v[36:37], v[196:197], v[200:201] op_sel:[0,1,0] op_sel_hi:[1,0,1]
	v_and_b32_e32 v203, 0xffff0000, v227
	v_cvt_pk_bf16_f32 v121, v194, v195
	v_cvt_pk_bf16_f32 v132, v196, v197
	v_lshlrev_b32_e32 v204, 16, v232
	ds_write_b32 v103, v121 offset:12960
	v_lshlrev_b32_e32 v205, 16, v236
	ds_write_b32 v103, v132 offset:15952
	v_pk_fma_f32 v[202:203], v[150:151], v[194:195], v[202:203]
	v_pk_fma_f32 v[204:205], v[152:153], v[196:197], v[204:205]
	v_lshlrev_b32_e32 v198, 16, v224
	v_pk_fma_f32 v[194:195], v[16:17], v[194:195], v[202:203] op_sel:[0,1,0] op_sel_hi:[1,0,1]
	v_pk_fma_f32 v[196:197], v[36:37], v[196:197], v[204:205] op_sel:[0,1,0] op_sel_hi:[1,0,1]
	v_lshlrev_b32_e32 v199, 16, v228
	v_cvt_pk_bf16_f32 v127, v194, v195
	v_cvt_pk_bf16_f32 v135, v196, v197
	v_and_b32_e32 v200, 0xffff0000, v231
	ds_write_b32 v103, v127 offset:13232
	v_and_b32_e32 v201, 0xffff0000, v235
	ds_write_b32 v103, v135 offset:15680
	v_pk_fma_f32 v[198:199], v[150:151], v[194:195], v[198:199]
	v_pk_fma_f32 v[200:201], v[152:153], v[196:197], v[200:201]
	v_and_b32_e32 v202, 0xffff0000, v224
	v_pk_fma_f32 v[194:195], v[16:17], v[194:195], v[198:199] op_sel:[0,1,0] op_sel_hi:[1,0,1]
	v_pk_fma_f32 v[196:197], v[36:37], v[196:197], v[200:201] op_sel:[0,1,0] op_sel_hi:[1,0,1]
	v_and_b32_e32 v203, 0xffff0000, v228
	v_cvt_pk_bf16_f32 v114, v194, v195
	v_cvt_pk_bf16_f32 v128, v196, v197
	v_lshlrev_b32_e32 v204, 16, v231
	ds_write_b32 v103, v114 offset:13504
	v_lshlrev_b32_e32 v205, 16, v235
	ds_write_b32 v103, v128 offset:15408
	v_pk_fma_f32 v[202:203], v[150:151], v[194:195], v[202:203]
	v_pk_fma_f32 v[204:205], v[152:153], v[196:197], v[204:205]
	v_lshlrev_b32_e32 v198, 16, v225
	v_pk_fma_f32 v[194:195], v[16:17], v[194:195], v[202:203] op_sel:[0,1,0] op_sel_hi:[1,0,1]
	v_pk_fma_f32 v[196:197], v[36:37], v[196:197], v[204:205] op_sel:[0,1,0] op_sel_hi:[1,0,1]
	v_lshlrev_b32_e32 v199, 16, v229
	v_cvt_pk_bf16_f32 v119, v194, v195
	v_cvt_pk_bf16_f32 v131, v196, v197
	v_and_b32_e32 v200, 0xffff0000, v230
	ds_write_b32 v103, v119 offset:13776
	v_and_b32_e32 v201, 0xffff0000, v234
	ds_write_b32 v103, v131 offset:15136
	v_pk_fma_f32 v[198:199], v[150:151], v[194:195], v[198:199]
	v_pk_fma_f32 v[200:201], v[152:153], v[196:197], v[200:201]
	v_and_b32_e32 v202, 0xffff0000, v225
	v_pk_fma_f32 v[194:195], v[16:17], v[194:195], v[198:199] op_sel:[0,1,0] op_sel_hi:[1,0,1]
	v_pk_fma_f32 v[196:197], v[36:37], v[196:197], v[200:201] op_sel:[0,1,0] op_sel_hi:[1,0,1]
	v_and_b32_e32 v203, 0xffff0000, v229
	v_cvt_pk_bf16_f32 v121, v194, v195
	v_cvt_pk_bf16_f32 v132, v196, v197
	v_lshlrev_b32_e32 v204, 16, v230
	ds_write_b32 v103, v121 offset:14048
	v_lshlrev_b32_e32 v205, 16, v234
	ds_write_b32 v103, v132 offset:14864
	v_pk_fma_f32 v[202:203], v[150:151], v[194:195], v[202:203]
	v_pk_fma_f32 v[204:205], v[152:153], v[196:197], v[204:205]
	s_waitcnt lgkmcnt(15)
; #define LAS __attribute__((address_space(3)))
; __device__ __forceinline__ void s5_out_phase(LAS unsigned char* lds, const bf16_t* UZ, const unsigned char* ws, const float* dskip, bf16_t* YG) {
;     ...
; #pragma unroll
;         for (int mm = 0; mm < 4; ++mm) {
;             const int mf = mm, mb = 3 - mm;
; #pragma unroll
;             for (int nt = 0; nt < 8; ++nt) {
;                 const f32x4 z = {0.f, 0.f, 0.f, 0.f};
;                 const f32x4 cf = __builtin_amdgcn_mfma_f32_16x16x16bf16_1k(Uf[mf], Bf[0][nt], z, 0, 0, 0);
;                 const f32x4 cb = __builtin_amdgcn_mfma_f32_16x16x16bf16_1k(Uf[mb], Bf[1][nt], z, 0, 0, 0);
;                 u32x2 wf, wb; wf.x = pk2(cf[0], cf[1]); wf.y = pk2(cf[2], cf[3]); wb.x = pk2(cb[0], cb[1]); wb.y = pk2(cb[2], cb[3]);
;                 *(LAS u32x2*)(wl + nt * 640 + wofs) = wf;
;                 *(LAS u32x2*)(wl + BUT_BYTES + nt * 640 + wofs) = wb;
;             }
;             WAVE_LDS_FENCE();
;             const LAS unsigned char* rp = wl + lane * 80;
;             const u32x4 fre0 = *(const LAS u32x4*)(rp), fre1 = *(const LAS u32x4*)(rp + 16), fim0 = *(const LAS u32x4*)(rp + 32), fim1 = *(const LAS u32x4*)(rp + 48);
;             const u32x4 bre0 = *(const LAS u32x4*)(rp + BUT_BYTES), bre1 = *(const LAS u32x4*)(rp + BUT_BYTES + 16), bim0 = *(const LAS u32x4*)(rp + BUT_BYTES + 32), bim1 = *(const LAS u32x4*)(rp + BUT_BYTES + 48);
;             LAS unsigned char* xf = wl + 2 * BUT_BYTES; LAS unsigned char* xbk = xf + XB_BYTES;
; #pragma unroll
;             for (int rr = 0; rr < 16; ++rr) {
;                 const int r = rr, rb = 15 - rr;
;                 { const f32x2 bb = {bf_at(fre0, fre1, r), bf_at(fim0, fim1, r)};
;                   const f32x2 n2 = cmac((f32x2){xfr, xfi}, (f32x2){ap[0].x, ap[0].x}, (f32x2){-ap[0].y, ap[0].y}, bb); xfr = n2.x; xfi = n2.y;
;                   *(LAS unsigned*)(xf + r * XB_PITCH + lane * 4) = pk2(n2.x, n2.y); }
;                 { const f32x2 bb = {bf_at(bre0, bre1, rb), bf_at(bim0, bim1, rb)};
;                   const f32x2 n2 = cmac((f32x2){xbr, xbi}, (f32x2){ap[1].x, ap[1].x}, (f32x2){-ap[1].y, ap[1].y}, bb); xbr = n2.x; xbi = n2.y;
;                   *(LAS unsigned*)(xbk + rb * XB_PITCH + lane * 4) = pk2(n2.x, n2.y); }
;             }
;             WAVE_LDS_FENCE();
; #pragma unroll
;             for (int ks = 0; ks < 4; ++ks) {
	v_lshlrev_b32_e32 v198, 16, v206
	v_pk_fma_f32 v[194:195], v[16:17], v[194:195], v[202:203] op_sel:[0,1,0] op_sel_hi:[1,0,1]
	v_pk_fma_f32 v[196:197], v[36:37], v[196:197], v[204:205] op_sel:[0,1,0] op_sel_hi:[1,0,1]
	v_lshlrev_b32_e32 v199, 16, v210
	v_cvt_pk_bf16_f32 v127, v194, v195
	v_cvt_pk_bf16_f32 v135, v196, v197
	v_and_b32_e32 v200, 0xffff0000, v217
	ds_write_b32 v103, v127 offset:14320
	v_and_b32_e32 v201, 0xffff0000, v221
	ds_write_b32 v103, v135 offset:14592
	ds_read_b128 v[222:225], v110 offset:10240
	ds_read_b128 v[226:229], v110 offset:10304
	ds_read_b128 v[230:233], v110 offset:10368
	ds_read_b128 v[234:237], v110 offset:10432
	ds_read_b128 v[238:241], v110 offset:14592
	ds_read_b128 v[242:245], v110 offset:14656
	ds_read_b128 v[246:249], v110 offset:14720
	ds_read_b128 v[250:253], v110 offset:14784
	v_pk_fma_f32 v[198:199], v[150:151], v[194:195], v[198:199]
	v_pk_fma_f32 v[200:201], v[152:153], v[196:197], v[200:201]
	v_and_b32_e32 v202, 0xffff0000, v206
	v_pk_fma_f32 v[194:195], v[16:17], v[194:195], v[198:199] op_sel:[0,1,0] op_sel_hi:[1,0,1]
	v_pk_fma_f32 v[196:197], v[36:37], v[196:197], v[200:201] op_sel:[0,1,0] op_sel_hi:[1,0,1]
	v_and_b32_e32 v203, 0xffff0000, v210
	v_cvt_pk_bf16_f32 v114, v194, v195
	v_cvt_pk_bf16_f32 v128, v196, v197
	v_lshlrev_b32_e32 v204, 16, v217
	ds_write_b32 v103, v114 offset:10240
	v_lshlrev_b32_e32 v205, 16, v221
	ds_write_b32 v103, v128 offset:18672
	v_pk_fma_f32 v[202:203], v[150:151], v[194:195], v[202:203]
	v_pk_fma_f32 v[204:205], v[152:153], v[196:197], v[204:205]
	v_lshlrev_b32_e32 v198, 16, v207
	v_pk_fma_f32 v[194:195], v[16:17], v[194:195], v[202:203] op_sel:[0,1,0] op_sel_hi:[1,0,1]
	v_pk_fma_f32 v[196:197], v[36:37], v[196:197], v[204:205] op_sel:[0,1,0] op_sel_hi:[1,0,1]
	v_lshlrev_b32_e32 v199, 16, v211
	v_cvt_pk_bf16_f32 v119, v194, v195
	v_cvt_pk_bf16_f32 v131, v196, v197
	v_and_b32_e32 v200, 0xffff0000, v216
	ds_write_b32 v103, v119 offset:10512
	v_and_b32_e32 v201, 0xffff0000, v220
	ds_write_b32 v103, v131 offset:18400
	v_pk_fma_f32 v[198:199], v[150:151], v[194:195], v[198:199]
	v_pk_fma_f32 v[200:201], v[152:153], v[196:197], v[200:201]
	v_and_b32_e32 v202, 0xffff0000, v207
	v_pk_fma_f32 v[194:195], v[16:17], v[194:195], v[198:199] op_sel:[0,1,0] op_sel_hi:[1,0,1]
	v_pk_fma_f32 v[196:197], v[36:37], v[196:197], v[200:201] op_sel:[0,1,0] op_sel_hi:[1,0,1]
	s_waitcnt lgkmcnt(11)
	v_mfma_f32_16x16x32_bf16 v[48:51], v[0:3], v[222:225], 0
	v_and_b32_e32 v203, 0xffff0000, v211
	v_cvt_pk_bf16_f32 v121, v194, v195
	v_cvt_pk_bf16_f32 v132, v196, v197
	s_waitcnt lgkmcnt(7)
	v_mfma_f32_16x16x32_bf16 v[44:47], v[20:23], v[238:241], 0
	v_lshlrev_b32_e32 v204, 16, v216
	ds_write_b32 v103, v121 offset:10784
	v_lshlrev_b32_e32 v205, 16, v220
	ds_write_b32 v103, v132 offset:18128
	v_mfma_f32_16x16x32_bf16 v[48:51], v[4:7], v[226:229], v[48:51]
	v_pk_fma_f32 v[202:203], v[150:151], v[194:195], v[202:203]
	v_pk_fma_f32 v[204:205], v[152:153], v[196:197], v[204:205]
	v_lshlrev_b32_e32 v198, 16, v208
	v_pk_fma_f32 v[194:195], v[16:17], v[194:195], v[202:203] op_sel:[0,1,0] op_sel_hi:[1,0,1]
	v_pk_fma_f32 v[196:197], v[36:37], v[196:197], v[204:205] op_sel:[0,1,0] op_sel_hi:[1,0,1]
	s_waitcnt lgkmcnt(8)
	v_mfma_f32_16x16x32_bf16 v[44:47], v[24:27], v[242:245], v[44:47]
	v_lshlrev_b32_e32 v199, 16, v212
	v_cvt_pk_bf16_f32 v127, v194, v195
	v_cvt_pk_bf16_f32 v135, v196, v197
	v_mfma_f32_16x16x32_bf16 v[48:51], v[8:11], v[230:233], v[48:51]
	v_and_b32_e32 v200, 0xffff0000, v215
	ds_write_b32 v103, v127 offset:11056
	v_and_b32_e32 v201, 0xffff0000, v219
	ds_write_b32 v103, v135 offset:17856
	s_waitcnt lgkmcnt(9)
	v_mfma_f32_16x16x32_bf16 v[44:47], v[28:31], v[246:249], v[44:47]
	v_pk_fma_f32 v[198:199], v[150:151], v[194:195], v[198:199]
	v_pk_fma_f32 v[200:201], v[152:153], v[196:197], v[200:201]
	v_and_b32_e32 v202, 0xffff0000, v208
	v_pk_fma_f32 v[194:195], v[16:17], v[194:195], v[198:199] op_sel:[0,1,0] op_sel_hi:[1,0,1]
	v_pk_fma_f32 v[196:197], v[36:37], v[196:197], v[200:201] op_sel:[0,1,0] op_sel_hi:[1,0,1]
	v_mfma_f32_16x16x32_bf16 v[48:51], v[12:15], v[234:237], v[48:51]
	v_and_b32_e32 v203, 0xffff0000, v212
	v_cvt_pk_bf16_f32 v114, v194, v195
	v_cvt_pk_bf16_f32 v128, v196, v197
	s_waitcnt lgkmcnt(8)
	v_mfma_f32_16x16x32_bf16 v[44:47], v[32:35], v[250:253], v[44:47]
	v_lshlrev_b32_e32 v204, 16, v215
	ds_write_b32 v103, v114 offset:11328
	v_lshlrev_b32_e32 v205, 16, v219
	ds_write_b32 v103, v128 offset:17584
	ds_read_b128 v[222:225], v109 offset:16
	ds_read_b128 v[226:229], v109 offset:48
	ds_read_b128 v[230:233], v109 offset:5120
	ds_read_b128 v[234:237], v109 offset:5152
	v_pk_fma_f32 v[202:203], v[150:151], v[194:195], v[202:203]
	v_pk_fma_f32 v[204:205], v[152:153], v[196:197], v[204:205]
	v_lshlrev_b32_e32 v198, 16, v209
	v_pk_fma_f32 v[194:195], v[16:17], v[194:195], v[202:203] op_sel:[0,1,0] op_sel_hi:[1,0,1]
	v_pk_fma_f32 v[196:197], v[36:37], v[196:197], v[204:205] op_sel:[0,1,0] op_sel_hi:[1,0,1]
	v_mfma_f32_16x16x16_bf16 v[238:241], v[168:169], v[60:61], 0
	v_lshlrev_b32_e32 v199, 16, v213
	v_cvt_pk_bf16_f32 v119, v194, v195
	v_cvt_pk_bf16_f32 v131, v196, v197
	v_mfma_f32_16x16x16_bf16 v[242:245], v[170:171], v[76:77], 0
	v_and_b32_e32 v200, 0xffff0000, v214
	ds_write_b32 v103, v119 offset:11600
	v_and_b32_e32 v201, 0xffff0000, v218
	ds_write_b32 v103, v131 offset:17312
	v_cvt_pk_bf16_f32 v238, v238, v239
	v_cvt_pk_bf16_f32 v239, v240, v241
	ds_write_b64 v104, v[238:239]
	v_mfma_f32_16x16x16_bf16 v[246:249], v[168:169], v[62:63], 0
	v_pk_fma_f32 v[198:199], v[150:151], v[194:195], v[198:199]
	v_pk_fma_f32 v[200:201], v[152:153], v[196:197], v[200:201]
	v_and_b32_e32 v202, 0xffff0000, v209
	v_pk_fma_f32 v[194:195], v[16:17], v[194:195], v[198:199] op_sel:[0,1,0] op_sel_hi:[1,0,1]
	v_pk_fma_f32 v[196:197], v[36:37], v[196:197], v[200:201] op_sel:[0,1,0] op_sel_hi:[1,0,1]
	v_cvt_pk_bf16_f32 v242, v242, v243
	v_cvt_pk_bf16_f32 v243, v244, v245
	ds_write_b64 v104, v[242:243] offset:5120
	v_mfma_f32_16x16x16_bf16 v[250:253], v[170:171], v[78:79], 0
	v_and_b32_e32 v203, 0xffff0000, v213
	v_cvt_pk_bf16_f32 v121, v194, v195
	v_cvt_pk_bf16_f32 v132, v196, v197
	v_cvt_pk_bf16_f32 v246, v246, v247
	v_cvt_pk_bf16_f32 v247, v248, v249
	ds_write_b64 v104, v[246:247] offset:640
	v_mfma_f32_16x16x16_bf16 v[238:241], v[168:169], v[64:65], 0
	v_lshlrev_b32_e32 v204, 16, v214
	ds_write_b32 v103, v121 offset:11872
	v_lshlrev_b32_e32 v205, 16, v218
	ds_write_b32 v103, v132 offset:17040
	v_cvt_pk_bf16_f32 v250, v250, v251
	v_cvt_pk_bf16_f32 v251, v252, v253
	ds_write_b64 v104, v[250:251] offset:5760
	v_mfma_f32_16x16x16_bf16 v[242:245], v[170:171], v[80:81], 0
	v_pk_fma_f32 v[202:203], v[150:151], v[194:195], v[202:203]
	v_pk_fma_f32 v[204:205], v[152:153], v[196:197], v[204:205]
	s_waitcnt lgkmcnt(11)
; #define LAS __attribute__((address_space(3)))
; #define WAVE_LDS_FENCE() asm volatile("s_waitcnt lgkmcnt(0)" ::: "memory")
; __device__ __forceinline__ void s5_out_phase(LAS unsigned char* lds, const bf16_t* UZ, const unsigned char* ws, const float* dskip, bf16_t* YG) {
;     ...
; #pragma unroll
;         for (int mm = 0; mm < 4; ++mm) {
;             const int mf = mm, mb = 3 - mm;
; #pragma unroll
;             for (int nt = 0; nt < 8; ++nt) {
;                 const f32x4 z = {0.f, 0.f, 0.f, 0.f};
;                 const f32x4 cf = __builtin_amdgcn_mfma_f32_16x16x16bf16_1k(Uf[mf], Bf[0][nt], z, 0, 0, 0);
;                 const f32x4 cb = __builtin_amdgcn_mfma_f32_16x16x16bf16_1k(Uf[mb], Bf[1][nt], z, 0, 0, 0);
;                 u32x2 wf, wb; wf.x = pk2(cf[0], cf[1]); wf.y = pk2(cf[2], cf[3]); wb.x = pk2(cb[0], cb[1]); wb.y = pk2(cb[2], cb[3]);
;                 *(LAS u32x2*)(wl + nt * 640 + wofs) = wf;
;                 *(LAS u32x2*)(wl + BUT_BYTES + nt * 640 + wofs) = wb;
;             }
;             WAVE_LDS_FENCE();
;             const LAS unsigned char* rp = wl + lane * 80;
;             const u32x4 fre0 = *(const LAS u32x4*)(rp), fre1 = *(const LAS u32x4*)(rp + 16), fim0 = *(const LAS u32x4*)(rp + 32), fim1 = *(const LAS u32x4*)(rp + 48);
;             const u32x4 bre0 = *(const LAS u32x4*)(rp + BUT_BYTES), bre1 = *(const LAS u32x4*)(rp + BUT_BYTES + 16), bim0 = *(const LAS u32x4*)(rp + BUT_BYTES + 32), bim1 = *(const LAS u32x4*)(rp + BUT_BYTES + 48);
;             LAS unsigned char* xf = wl + 2 * BUT_BYTES; LAS unsigned char* xbk = xf + XB_BYTES;
; #pragma unroll
;             for (int rr = 0; rr < 16; ++rr) {
;                 const int r = rr, rb = 15 - rr;
;                 { const f32x2 bb = {bf_at(fre0, fre1, r), bf_at(fim0, fim1, r)};
;                   const f32x2 n2 = cmac((f32x2){xfr, xfi}, (f32x2){ap[0].x, ap[0].x}, (f32x2){-ap[0].y, ap[0].y}, bb); xfr = n2.x; xfi = n2.y;
;                   *(LAS unsigned*)(xf + r * XB_PITCH + lane * 4) = pk2(n2.x, n2.y); }
;                 { const f32x2 bb = {bf_at(bre0, bre1, rb), bf_at(bim0, bim1, rb)};
;                   const f32x2 n2 = cmac((f32x2){xbr, xbi}, (f32x2){ap[1].x, ap[1].x}, (f32x2){-ap[1].y, ap[1].y}, bb); xbr = n2.x; xbi = n2.y;
;                   *(LAS unsigned*)(xbk + rb * XB_PITCH + lane * 4) = pk2(n2.x, n2.y); }
;             }
;             WAVE_LDS_FENCE();
	v_lshlrev_b32_e32 v198, 16, v222
	v_pk_fma_f32 v[194:195], v[16:17], v[194:195], v[202:203] op_sel:[0,1,0] op_sel_hi:[1,0,1]
	v_pk_fma_f32 v[196:197], v[36:37], v[196:197], v[204:205] op_sel:[0,1,0] op_sel_hi:[1,0,1]
	v_cvt_pk_bf16_f32 v238, v238, v239
	v_cvt_pk_bf16_f32 v239, v240, v241
	ds_write_b64 v104, v[238:239] offset:1280
	v_mfma_f32_16x16x16_bf16 v[246:249], v[168:169], v[66:67], 0
	s_waitcnt lgkmcnt(11)
	v_lshlrev_b32_e32 v199, 16, v226
	v_cvt_pk_bf16_f32 v127, v194, v195
	v_cvt_pk_bf16_f32 v135, v196, v197
	v_cvt_pk_bf16_f32 v242, v242, v243
	v_cvt_pk_bf16_f32 v243, v244, v245
	ds_write_b64 v104, v[242:243] offset:6400
	v_mfma_f32_16x16x16_bf16 v[250:253], v[170:171], v[82:83], 0
	s_waitcnt lgkmcnt(11)
	v_and_b32_e32 v200, 0xffff0000, v233
	ds_write_b32 v103, v127 offset:12144
	s_waitcnt lgkmcnt(11)
	v_and_b32_e32 v201, 0xffff0000, v237
	ds_write_b32 v103, v135 offset:16768
	v_cvt_pk_bf16_f32 v246, v246, v247
	v_cvt_pk_bf16_f32 v247, v248, v249
	ds_write_b64 v104, v[246:247] offset:1920
	v_mfma_f32_16x16x16_bf16 v[238:241], v[168:169], v[68:69], 0
	v_pk_fma_f32 v[198:199], v[150:151], v[194:195], v[198:199]
	v_pk_fma_f32 v[200:201], v[152:153], v[196:197], v[200:201]
	v_and_b32_e32 v202, 0xffff0000, v222
	v_pk_fma_f32 v[194:195], v[16:17], v[194:195], v[198:199] op_sel:[0,1,0] op_sel_hi:[1,0,1]
	v_pk_fma_f32 v[196:197], v[36:37], v[196:197], v[200:201] op_sel:[0,1,0] op_sel_hi:[1,0,1]
	v_cvt_pk_bf16_f32 v250, v250, v251
	v_cvt_pk_bf16_f32 v251, v252, v253
	ds_write_b64 v104, v[250:251] offset:7040
	v_mfma_f32_16x16x16_bf16 v[242:245], v[170:171], v[84:85], 0
	v_and_b32_e32 v203, 0xffff0000, v226
	v_cvt_pk_bf16_f32 v114, v194, v195
	v_cvt_pk_bf16_f32 v128, v196, v197
	v_cvt_pk_bf16_f32 v238, v238, v239
	v_cvt_pk_bf16_f32 v239, v240, v241
	ds_write_b64 v104, v[238:239] offset:2560
	v_mfma_f32_16x16x16_bf16 v[246:249], v[168:169], v[70:71], 0
	v_lshlrev_b32_e32 v204, 16, v233
	ds_write_b32 v103, v114 offset:12416
	v_lshlrev_b32_e32 v205, 16, v237
	ds_write_b32 v103, v128 offset:16496
	v_cvt_pk_bf16_f32 v242, v242, v243
	v_cvt_pk_bf16_f32 v243, v244, v245
	ds_write_b64 v104, v[242:243] offset:7680
	v_mfma_f32_16x16x16_bf16 v[250:253], v[170:171], v[86:87], 0
	v_pk_fma_f32 v[202:203], v[150:151], v[194:195], v[202:203]
	v_pk_fma_f32 v[204:205], v[152:153], v[196:197], v[204:205]
	v_lshlrev_b32_e32 v198, 16, v223
	v_pk_fma_f32 v[194:195], v[16:17], v[194:195], v[202:203] op_sel:[0,1,0] op_sel_hi:[1,0,1]
	v_pk_fma_f32 v[196:197], v[36:37], v[196:197], v[204:205] op_sel:[0,1,0] op_sel_hi:[1,0,1]
	v_cvt_pk_bf16_f32 v246, v246, v247
	v_cvt_pk_bf16_f32 v247, v248, v249
	ds_write_b64 v104, v[246:247] offset:3200
	v_mfma_f32_16x16x16_bf16 v[238:241], v[168:169], v[72:73], 0
	v_lshlrev_b32_e32 v199, 16, v227
	v_cvt_pk_bf16_f32 v119, v194, v195
	v_cvt_pk_bf16_f32 v131, v196, v197
	v_cvt_pk_bf16_f32 v250, v250, v251
	v_cvt_pk_bf16_f32 v251, v252, v253
	ds_write_b64 v104, v[250:251] offset:8320
	v_mfma_f32_16x16x16_bf16 v[242:245], v[170:171], v[88:89], 0
	v_and_b32_e32 v200, 0xffff0000, v232
	ds_write_b32 v103, v119 offset:12688
	v_and_b32_e32 v201, 0xffff0000, v236
	ds_write_b32 v103, v131 offset:16224
	v_cvt_pk_bf16_f32 v238, v238, v239
	v_cvt_pk_bf16_f32 v239, v240, v241
	ds_write_b64 v104, v[238:239] offset:3840
	v_mfma_f32_16x16x16_bf16 v[246:249], v[168:169], v[74:75], 0
	v_pk_fma_f32 v[198:199], v[150:151], v[194:195], v[198:199]
	v_pk_fma_f32 v[200:201], v[152:153], v[196:197], v[200:201]
	v_and_b32_e32 v202, 0xffff0000, v223
	v_pk_fma_f32 v[194:195], v[16:17], v[194:195], v[198:199] op_sel:[0,1,0] op_sel_hi:[1,0,1]
	v_pk_fma_f32 v[196:197], v[36:37], v[196:197], v[200:201] op_sel:[0,1,0] op_sel_hi:[1,0,1]
	v_cvt_pk_bf16_f32 v242, v242, v243
	v_cvt_pk_bf16_f32 v243, v244, v245
	ds_write_b64 v104, v[242:243] offset:8960
	v_mfma_f32_16x16x16_bf16 v[250:253], v[170:171], v[90:91], 0
	v_and_b32_e32 v203, 0xffff0000, v227
	v_cvt_pk_bf16_f32 v121, v194, v195
	v_cvt_pk_bf16_f32 v132, v196, v197
	v_cvt_pk_bf16_f32 v246, v246, v247
	v_cvt_pk_bf16_f32 v247, v248, v249
	ds_write_b64 v104, v[246:247] offset:4480
	v_lshlrev_b32_e32 v204, 16, v232
	ds_write_b32 v103, v121 offset:12960
	v_lshlrev_b32_e32 v205, 16, v236
	ds_write_b32 v103, v132 offset:15952
	v_cvt_pk_bf16_f32 v250, v250, v251
	v_cvt_pk_bf16_f32 v251, v252, v253
	ds_write_b64 v104, v[250:251] offset:9600
	v_pk_fma_f32 v[202:203], v[150:151], v[194:195], v[202:203]
	v_pk_fma_f32 v[204:205], v[152:153], v[196:197], v[204:205]
	v_lshlrev_b32_e32 v198, 16, v224
	v_pk_fma_f32 v[194:195], v[16:17], v[194:195], v[202:203] op_sel:[0,1,0] op_sel_hi:[1,0,1]
	v_pk_fma_f32 v[196:197], v[36:37], v[196:197], v[204:205] op_sel:[0,1,0] op_sel_hi:[1,0,1]
	ds_read_b128 v[206:209], v109
	ds_read_b128 v[210:213], v109 offset:32
	ds_read_b128 v[214:217], v109 offset:5136
	ds_read_b128 v[218:221], v109 offset:5168
	v_lshlrev_b32_e32 v199, 16, v228
	v_cvt_pk_bf16_f32 v127, v194, v195
	v_cvt_pk_bf16_f32 v135, v196, v197
	v_and_b32_e32 v200, 0xffff0000, v231
	ds_write_b32 v103, v127 offset:13232
	v_and_b32_e32 v201, 0xffff0000, v235
	ds_write_b32 v103, v135 offset:15680
	v_pk_fma_f32 v[198:199], v[150:151], v[194:195], v[198:199]
	v_pk_fma_f32 v[200:201], v[152:153], v[196:197], v[200:201]
	v_and_b32_e32 v202, 0xffff0000, v224
	v_pk_fma_f32 v[194:195], v[16:17], v[194:195], v[198:199] op_sel:[0,1,0] op_sel_hi:[1,0,1]
	v_pk_fma_f32 v[196:197], v[36:37], v[196:197], v[200:201] op_sel:[0,1,0] op_sel_hi:[1,0,1]
	v_and_b32_e32 v203, 0xffff0000, v228
	v_cvt_pk_bf16_f32 v114, v194, v195
	v_cvt_pk_bf16_f32 v128, v196, v197
	v_lshlrev_b32_e32 v204, 16, v231
	ds_write_b32 v103, v114 offset:13504
	v_lshlrev_b32_e32 v205, 16, v235
	ds_write_b32 v103, v128 offset:15408
	v_pk_fma_f32 v[202:203], v[150:151], v[194:195], v[202:203]
	v_pk_fma_f32 v[204:205], v[152:153], v[196:197], v[204:205]
	v_lshlrev_b32_e32 v198, 16, v225
	v_pk_fma_f32 v[194:195], v[16:17], v[194:195], v[202:203] op_sel:[0,1,0] op_sel_hi:[1,0,1]
	v_pk_fma_f32 v[196:197], v[36:37], v[196:197], v[204:205] op_sel:[0,1,0] op_sel_hi:[1,0,1]
	v_lshlrev_b32_e32 v199, 16, v229
	v_cvt_pk_bf16_f32 v119, v194, v195
	v_cvt_pk_bf16_f32 v131, v196, v197
	v_and_b32_e32 v200, 0xffff0000, v230
	ds_write_b32 v103, v119 offset:13776
	v_and_b32_e32 v201, 0xffff0000, v234
	ds_write_b32 v103, v131 offset:15136
	v_pk_fma_f32 v[198:199], v[150:151], v[194:195], v[198:199]
	v_pk_fma_f32 v[200:201], v[152:153], v[196:197], v[200:201]
	v_and_b32_e32 v202, 0xffff0000, v225
	v_pk_fma_f32 v[194:195], v[16:17], v[194:195], v[198:199] op_sel:[0,1,0] op_sel_hi:[1,0,1]
	v_pk_fma_f32 v[196:197], v[36:37], v[196:197], v[200:201] op_sel:[0,1,0] op_sel_hi:[1,0,1]
	v_and_b32_e32 v203, 0xffff0000, v229
	v_cvt_pk_bf16_f32 v121, v194, v195
	v_cvt_pk_bf16_f32 v132, v196, v197
	v_lshlrev_b32_e32 v204, 16, v230
	ds_write_b32 v103, v121 offset:14048
	v_lshlrev_b32_e32 v205, 16, v234
	ds_write_b32 v103, v132 offset:14864
	v_pk_fma_f32 v[202:203], v[150:151], v[194:195], v[202:203]
	v_pk_fma_f32 v[204:205], v[152:153], v[196:197], v[204:205]
	s_waitcnt lgkmcnt(11)
; #define LAS __attribute__((address_space(3)))
; __device__ __forceinline__ void s5_out_phase(LAS unsigned char* lds, const bf16_t* UZ, const unsigned char* ws, const float* dskip, bf16_t* YG) {
;     ...
; #pragma unroll
;         for (int mm = 0; mm < 4; ++mm) {
;             const int mf = mm, mb = 3 - mm;
; #pragma unroll
;             for (int nt = 0; nt < 8; ++nt) {
;                 const f32x4 z = {0.f, 0.f, 0.f, 0.f};
;                 const f32x4 cf = __builtin_amdgcn_mfma_f32_16x16x16bf16_1k(Uf[mf], Bf[0][nt], z, 0, 0, 0);
;                 const f32x4 cb = __builtin_amdgcn_mfma_f32_16x16x16bf16_1k(Uf[mb], Bf[1][nt], z, 0, 0, 0);
;                 u32x2 wf, wb; wf.x = pk2(cf[0], cf[1]); wf.y = pk2(cf[2], cf[3]); wb.x = pk2(cb[0], cb[1]); wb.y = pk2(cb[2], cb[3]);
;                 *(LAS u32x2*)(wl + nt * 640 + wofs) = wf;
;                 *(LAS u32x2*)(wl + BUT_BYTES + nt * 640 + wofs) = wb;
;             }
;             WAVE_LDS_FENCE();
;             const LAS unsigned char* rp = wl + lane * 80;
;             const u32x4 fre0 = *(const LAS u32x4*)(rp), fre1 = *(const LAS u32x4*)(rp + 16), fim0 = *(const LAS u32x4*)(rp + 32), fim1 = *(const LAS u32x4*)(rp + 48);
;             const u32x4 bre0 = *(const LAS u32x4*)(rp + BUT_BYTES), bre1 = *(const LAS u32x4*)(rp + BUT_BYTES + 16), bim0 = *(const LAS u32x4*)(rp + BUT_BYTES + 32), bim1 = *(const LAS u32x4*)(rp + BUT_BYTES + 48);
;             LAS unsigned char* xf = wl + 2 * BUT_BYTES; LAS unsigned char* xbk = xf + XB_BYTES;
; #pragma unroll
;             for (int rr = 0; rr < 16; ++rr) {
;                 const int r = rr, rb = 15 - rr;
;                 { const f32x2 bb = {bf_at(fre0, fre1, r), bf_at(fim0, fim1, r)};
;                   const f32x2 n2 = cmac((f32x2){xfr, xfi}, (f32x2){ap[0].x, ap[0].x}, (f32x2){-ap[0].y, ap[0].y}, bb); xfr = n2.x; xfi = n2.y;
;                   *(LAS unsigned*)(xf + r * XB_PITCH + lane * 4) = pk2(n2.x, n2.y); }
;                 { const f32x2 bb = {bf_at(bre0, bre1, rb), bf_at(bim0, bim1, rb)};
;                   const f32x2 n2 = cmac((f32x2){xbr, xbi}, (f32x2){ap[1].x, ap[1].x}, (f32x2){-ap[1].y, ap[1].y}, bb); xbr = n2.x; xbi = n2.y;
;                   *(LAS unsigned*)(xbk + rb * XB_PITCH + lane * 4) = pk2(n2.x, n2.y); }
;             }
;             WAVE_LDS_FENCE();
; #pragma unroll
;             for (int ks = 0; ks < 4; ++ks) {
	v_lshlrev_b32_e32 v198, 16, v206
	v_pk_fma_f32 v[194:195], v[16:17], v[194:195], v[202:203] op_sel:[0,1,0] op_sel_hi:[1,0,1]
	v_pk_fma_f32 v[196:197], v[36:37], v[196:197], v[204:205] op_sel:[0,1,0] op_sel_hi:[1,0,1]
	s_waitcnt lgkmcnt(10)
	v_lshlrev_b32_e32 v199, 16, v210
	v_cvt_pk_bf16_f32 v127, v194, v195
	v_cvt_pk_bf16_f32 v135, v196, v197
	s_waitcnt lgkmcnt(9)
	v_and_b32_e32 v200, 0xffff0000, v217
	ds_write_b32 v103, v127 offset:14320
	s_waitcnt lgkmcnt(9)
	v_and_b32_e32 v201, 0xffff0000, v221
	ds_write_b32 v103, v135 offset:14592
	ds_read_b128 v[222:225], v110 offset:10240
	ds_read_b128 v[226:229], v110 offset:10304
	ds_read_b128 v[230:233], v110 offset:10368
	ds_read_b128 v[234:237], v110 offset:10432
	ds_read_b128 v[238:241], v110 offset:14592
	ds_read_b128 v[242:245], v110 offset:14656
	ds_read_b128 v[246:249], v110 offset:14720
	ds_read_b128 v[250:253], v110 offset:14784
	v_pk_fma_f32 v[198:199], v[150:151], v[194:195], v[198:199]
	v_pk_fma_f32 v[200:201], v[152:153], v[196:197], v[200:201]
	v_and_b32_e32 v202, 0xffff0000, v206
	v_pk_fma_f32 v[194:195], v[16:17], v[194:195], v[198:199] op_sel:[0,1,0] op_sel_hi:[1,0,1]
	v_pk_fma_f32 v[196:197], v[36:37], v[196:197], v[200:201] op_sel:[0,1,0] op_sel_hi:[1,0,1]
	v_and_b32_e32 v203, 0xffff0000, v210
	v_cvt_pk_bf16_f32 v114, v194, v195
	v_cvt_pk_bf16_f32 v128, v196, v197
	v_lshlrev_b32_e32 v204, 16, v217
	ds_write_b32 v103, v114 offset:10240
	v_lshlrev_b32_e32 v205, 16, v221
	ds_write_b32 v103, v128 offset:18672
	v_pk_fma_f32 v[202:203], v[150:151], v[194:195], v[202:203]
	v_pk_fma_f32 v[204:205], v[152:153], v[196:197], v[204:205]
	v_lshlrev_b32_e32 v198, 16, v207
	v_pk_fma_f32 v[194:195], v[16:17], v[194:195], v[202:203] op_sel:[0,1,0] op_sel_hi:[1,0,1]
	v_pk_fma_f32 v[196:197], v[36:37], v[196:197], v[204:205] op_sel:[0,1,0] op_sel_hi:[1,0,1]
	v_lshlrev_b32_e32 v199, 16, v211
	v_cvt_pk_bf16_f32 v119, v194, v195
	v_cvt_pk_bf16_f32 v131, v196, v197
	v_and_b32_e32 v200, 0xffff0000, v216
	ds_write_b32 v103, v119 offset:10512
	v_and_b32_e32 v201, 0xffff0000, v220
	ds_write_b32 v103, v131 offset:18400
	v_pk_fma_f32 v[198:199], v[150:151], v[194:195], v[198:199]
	v_pk_fma_f32 v[200:201], v[152:153], v[196:197], v[200:201]
	v_and_b32_e32 v202, 0xffff0000, v207
	v_pk_fma_f32 v[194:195], v[16:17], v[194:195], v[198:199] op_sel:[0,1,0] op_sel_hi:[1,0,1]
	v_pk_fma_f32 v[196:197], v[36:37], v[196:197], v[200:201] op_sel:[0,1,0] op_sel_hi:[1,0,1]
	s_waitcnt lgkmcnt(11)
	v_mfma_f32_16x16x32_bf16 v[56:59], v[0:3], v[222:225], 0
	v_and_b32_e32 v203, 0xffff0000, v211
	v_cvt_pk_bf16_f32 v121, v194, v195
	v_cvt_pk_bf16_f32 v132, v196, v197
	s_waitcnt lgkmcnt(7)
	v_mfma_f32_16x16x32_bf16 v[52:55], v[20:23], v[238:241], 0
	v_lshlrev_b32_e32 v204, 16, v216
	ds_write_b32 v103, v121 offset:10784
	v_lshlrev_b32_e32 v205, 16, v220
	ds_write_b32 v103, v132 offset:18128
	v_mfma_f32_16x16x32_bf16 v[56:59], v[4:7], v[226:229], v[56:59]
	v_pk_fma_f32 v[202:203], v[150:151], v[194:195], v[202:203]
	v_pk_fma_f32 v[204:205], v[152:153], v[196:197], v[204:205]
	v_lshlrev_b32_e32 v198, 16, v208
	v_pk_fma_f32 v[194:195], v[16:17], v[194:195], v[202:203] op_sel:[0,1,0] op_sel_hi:[1,0,1]
	v_pk_fma_f32 v[196:197], v[36:37], v[196:197], v[204:205] op_sel:[0,1,0] op_sel_hi:[1,0,1]
	s_waitcnt lgkmcnt(8)
	v_mfma_f32_16x16x32_bf16 v[52:55], v[24:27], v[242:245], v[52:55]
	v_lshlrev_b32_e32 v199, 16, v212
	v_cvt_pk_bf16_f32 v127, v194, v195
	v_cvt_pk_bf16_f32 v135, v196, v197
	v_mfma_f32_16x16x32_bf16 v[56:59], v[8:11], v[230:233], v[56:59]
	v_and_b32_e32 v200, 0xffff0000, v215
	ds_write_b32 v103, v127 offset:11056
	v_and_b32_e32 v201, 0xffff0000, v219
	ds_write_b32 v103, v135 offset:17856
	s_waitcnt lgkmcnt(9)
	v_mfma_f32_16x16x32_bf16 v[52:55], v[28:31], v[246:249], v[52:55]
	v_pk_fma_f32 v[198:199], v[150:151], v[194:195], v[198:199]
	v_pk_fma_f32 v[200:201], v[152:153], v[196:197], v[200:201]
	v_and_b32_e32 v202, 0xffff0000, v208
	v_pk_fma_f32 v[194:195], v[16:17], v[194:195], v[198:199] op_sel:[0,1,0] op_sel_hi:[1,0,1]
	v_pk_fma_f32 v[196:197], v[36:37], v[196:197], v[200:201] op_sel:[0,1,0] op_sel_hi:[1,0,1]
	v_mfma_f32_16x16x32_bf16 v[56:59], v[12:15], v[234:237], v[56:59]
	v_and_b32_e32 v203, 0xffff0000, v212
	v_cvt_pk_bf16_f32 v114, v194, v195
	v_cvt_pk_bf16_f32 v128, v196, v197
	s_waitcnt lgkmcnt(8)
	v_mfma_f32_16x16x32_bf16 v[52:55], v[32:35], v[250:253], v[52:55]
	v_lshlrev_b32_e32 v204, 16, v215
	ds_write_b32 v103, v114 offset:11328
	v_lshlrev_b32_e32 v205, 16, v219
	ds_write_b32 v103, v128 offset:17584
	ds_read_b128 v[222:225], v109 offset:16
	ds_read_b128 v[226:229], v109 offset:48
	ds_read_b128 v[230:233], v109 offset:5120
	ds_read_b128 v[234:237], v109 offset:5152
	v_pk_fma_f32 v[202:203], v[150:151], v[194:195], v[202:203]
	v_pk_fma_f32 v[204:205], v[152:153], v[196:197], v[204:205]
	v_lshlrev_b32_e32 v198, 16, v209
	v_pk_fma_f32 v[194:195], v[16:17], v[194:195], v[202:203] op_sel:[0,1,0] op_sel_hi:[1,0,1]
	v_pk_fma_f32 v[196:197], v[36:37], v[196:197], v[204:205] op_sel:[0,1,0] op_sel_hi:[1,0,1]
	v_mfma_f32_16x16x16_bf16 v[238:241], v[116:117], v[60:61], 0
	v_lshlrev_b32_e32 v199, 16, v213
	v_cvt_pk_bf16_f32 v119, v194, v195
	v_cvt_pk_bf16_f32 v131, v196, v197
	v_mfma_f32_16x16x16_bf16 v[242:245], v[172:173], v[76:77], 0
	v_and_b32_e32 v200, 0xffff0000, v214
	ds_write_b32 v103, v119 offset:11600
	v_and_b32_e32 v201, 0xffff0000, v218
	ds_write_b32 v103, v131 offset:17312
	v_cvt_pk_bf16_f32 v238, v238, v239
	v_cvt_pk_bf16_f32 v239, v240, v241
	ds_write_b64 v104, v[238:239]
	v_mfma_f32_16x16x16_bf16 v[246:249], v[116:117], v[62:63], 0
	v_pk_fma_f32 v[198:199], v[150:151], v[194:195], v[198:199]
	v_pk_fma_f32 v[200:201], v[152:153], v[196:197], v[200:201]
	v_and_b32_e32 v202, 0xffff0000, v209
	v_pk_fma_f32 v[194:195], v[16:17], v[194:195], v[198:199] op_sel:[0,1,0] op_sel_hi:[1,0,1]
	v_pk_fma_f32 v[196:197], v[36:37], v[196:197], v[200:201] op_sel:[0,1,0] op_sel_hi:[1,0,1]
	v_cvt_pk_bf16_f32 v242, v242, v243
	v_cvt_pk_bf16_f32 v243, v244, v245
	ds_write_b64 v104, v[242:243] offset:5120
	v_mfma_f32_16x16x16_bf16 v[250:253], v[172:173], v[78:79], 0
	v_and_b32_e32 v203, 0xffff0000, v213
	v_cvt_pk_bf16_f32 v121, v194, v195
	v_cvt_pk_bf16_f32 v132, v196, v197
	v_cvt_pk_bf16_f32 v246, v246, v247
	v_cvt_pk_bf16_f32 v247, v248, v249
	ds_write_b64 v104, v[246:247] offset:640
	v_mfma_f32_16x16x16_bf16 v[238:241], v[116:117], v[64:65], 0
	v_lshlrev_b32_e32 v204, 16, v214
	ds_write_b32 v103, v121 offset:11872
	v_lshlrev_b32_e32 v205, 16, v218
	ds_write_b32 v103, v132 offset:17040
	v_cvt_pk_bf16_f32 v250, v250, v251
	v_cvt_pk_bf16_f32 v251, v252, v253
	ds_write_b64 v104, v[250:251] offset:5760
	v_mfma_f32_16x16x16_bf16 v[242:245], v[172:173], v[80:81], 0
	v_pk_fma_f32 v[202:203], v[150:151], v[194:195], v[202:203]
	v_pk_fma_f32 v[204:205], v[152:153], v[196:197], v[204:205]
	s_waitcnt lgkmcnt(11)
; #define LAS __attribute__((address_space(3)))
; #define WAVE_LDS_FENCE() asm volatile("s_waitcnt lgkmcnt(0)" ::: "memory")
; __device__ __forceinline__ void s5_out_phase(LAS unsigned char* lds, const bf16_t* UZ, const unsigned char* ws, const float* dskip, bf16_t* YG) {
;     ...
; #pragma unroll
;         for (int mm = 0; mm < 4; ++mm) {
;             const int mf = mm, mb = 3 - mm;
; #pragma unroll
;             for (int nt = 0; nt < 8; ++nt) {
;                 const f32x4 z = {0.f, 0.f, 0.f, 0.f};
;                 const f32x4 cf = __builtin_amdgcn_mfma_f32_16x16x16bf16_1k(Uf[mf], Bf[0][nt], z, 0, 0, 0);
;                 const f32x4 cb = __builtin_amdgcn_mfma_f32_16x16x16bf16_1k(Uf[mb], Bf[1][nt], z, 0, 0, 0);
;                 u32x2 wf, wb; wf.x = pk2(cf[0], cf[1]); wf.y = pk2(cf[2], cf[3]); wb.x = pk2(cb[0], cb[1]); wb.y = pk2(cb[2], cb[3]);
;                 *(LAS u32x2*)(wl + nt * 640 + wofs) = wf;
;                 *(LAS u32x2*)(wl + BUT_BYTES + nt * 640 + wofs) = wb;
;             }
;             WAVE_LDS_FENCE();
;             const LAS unsigned char* rp = wl + lane * 80;
;             const u32x4 fre0 = *(const LAS u32x4*)(rp), fre1 = *(const LAS u32x4*)(rp + 16), fim0 = *(const LAS u32x4*)(rp + 32), fim1 = *(const LAS u32x4*)(rp + 48);
;             const u32x4 bre0 = *(const LAS u32x4*)(rp + BUT_BYTES), bre1 = *(const LAS u32x4*)(rp + BUT_BYTES + 16), bim0 = *(const LAS u32x4*)(rp + BUT_BYTES + 32), bim1 = *(const LAS u32x4*)(rp + BUT_BYTES + 48);
;             LAS unsigned char* xf = wl + 2 * BUT_BYTES; LAS unsigned char* xbk = xf + XB_BYTES;
; #pragma unroll
;             for (int rr = 0; rr < 16; ++rr) {
;                 const int r = rr, rb = 15 - rr;
;                 { const f32x2 bb = {bf_at(fre0, fre1, r), bf_at(fim0, fim1, r)};
;                   const f32x2 n2 = cmac((f32x2){xfr, xfi}, (f32x2){ap[0].x, ap[0].x}, (f32x2){-ap[0].y, ap[0].y}, bb); xfr = n2.x; xfi = n2.y;
;                   *(LAS unsigned*)(xf + r * XB_PITCH + lane * 4) = pk2(n2.x, n2.y); }
;                 { const f32x2 bb = {bf_at(bre0, bre1, rb), bf_at(bim0, bim1, rb)};
;                   const f32x2 n2 = cmac((f32x2){xbr, xbi}, (f32x2){ap[1].x, ap[1].x}, (f32x2){-ap[1].y, ap[1].y}, bb); xbr = n2.x; xbi = n2.y;
;                   *(LAS unsigned*)(xbk + rb * XB_PITCH + lane * 4) = pk2(n2.x, n2.y); }
;             }
;             WAVE_LDS_FENCE();
	v_lshlrev_b32_e32 v198, 16, v222
	v_pk_fma_f32 v[194:195], v[16:17], v[194:195], v[202:203] op_sel:[0,1,0] op_sel_hi:[1,0,1]
	v_pk_fma_f32 v[196:197], v[36:37], v[196:197], v[204:205] op_sel:[0,1,0] op_sel_hi:[1,0,1]
	v_cvt_pk_bf16_f32 v238, v238, v239
	v_cvt_pk_bf16_f32 v239, v240, v241
	ds_write_b64 v104, v[238:239] offset:1280
	v_mfma_f32_16x16x16_bf16 v[246:249], v[116:117], v[66:67], 0
	s_waitcnt lgkmcnt(11)
	v_lshlrev_b32_e32 v199, 16, v226
	v_cvt_pk_bf16_f32 v127, v194, v195
	v_cvt_pk_bf16_f32 v135, v196, v197
	v_cvt_pk_bf16_f32 v242, v242, v243
	v_cvt_pk_bf16_f32 v243, v244, v245
	ds_write_b64 v104, v[242:243] offset:6400
	v_mfma_f32_16x16x16_bf16 v[250:253], v[172:173], v[82:83], 0
	s_waitcnt lgkmcnt(11)
	v_and_b32_e32 v200, 0xffff0000, v233
	ds_write_b32 v103, v127 offset:12144
	s_waitcnt lgkmcnt(11)
	v_and_b32_e32 v201, 0xffff0000, v237
	ds_write_b32 v103, v135 offset:16768
	v_cvt_pk_bf16_f32 v246, v246, v247
	v_cvt_pk_bf16_f32 v247, v248, v249
	ds_write_b64 v104, v[246:247] offset:1920
	v_mfma_f32_16x16x16_bf16 v[238:241], v[116:117], v[68:69], 0
	v_pk_fma_f32 v[198:199], v[150:151], v[194:195], v[198:199]
	v_pk_fma_f32 v[200:201], v[152:153], v[196:197], v[200:201]
	v_and_b32_e32 v202, 0xffff0000, v222
	v_pk_fma_f32 v[194:195], v[16:17], v[194:195], v[198:199] op_sel:[0,1,0] op_sel_hi:[1,0,1]
	v_pk_fma_f32 v[196:197], v[36:37], v[196:197], v[200:201] op_sel:[0,1,0] op_sel_hi:[1,0,1]
	v_cvt_pk_bf16_f32 v250, v250, v251
	v_cvt_pk_bf16_f32 v251, v252, v253
	ds_write_b64 v104, v[250:251] offset:7040
	v_mfma_f32_16x16x16_bf16 v[242:245], v[172:173], v[84:85], 0
	v_and_b32_e32 v203, 0xffff0000, v226
	v_cvt_pk_bf16_f32 v114, v194, v195
	v_cvt_pk_bf16_f32 v128, v196, v197
	v_cvt_pk_bf16_f32 v238, v238, v239
	v_cvt_pk_bf16_f32 v239, v240, v241
	ds_write_b64 v104, v[238:239] offset:2560
	v_mfma_f32_16x16x16_bf16 v[246:249], v[116:117], v[70:71], 0
	v_lshlrev_b32_e32 v204, 16, v233
	ds_write_b32 v103, v114 offset:12416
	v_lshlrev_b32_e32 v205, 16, v237
	ds_write_b32 v103, v128 offset:16496
	v_cvt_pk_bf16_f32 v242, v242, v243
	v_cvt_pk_bf16_f32 v243, v244, v245
	ds_write_b64 v104, v[242:243] offset:7680
	v_mfma_f32_16x16x16_bf16 v[250:253], v[172:173], v[86:87], 0
	v_pk_fma_f32 v[202:203], v[150:151], v[194:195], v[202:203]
	v_pk_fma_f32 v[204:205], v[152:153], v[196:197], v[204:205]
	v_lshlrev_b32_e32 v198, 16, v223
	v_pk_fma_f32 v[194:195], v[16:17], v[194:195], v[202:203] op_sel:[0,1,0] op_sel_hi:[1,0,1]
	v_pk_fma_f32 v[196:197], v[36:37], v[196:197], v[204:205] op_sel:[0,1,0] op_sel_hi:[1,0,1]
	v_cvt_pk_bf16_f32 v246, v246, v247
	v_cvt_pk_bf16_f32 v247, v248, v249
	ds_write_b64 v104, v[246:247] offset:3200
	v_mfma_f32_16x16x16_bf16 v[238:241], v[116:117], v[72:73], 0
	v_lshlrev_b32_e32 v199, 16, v227
	v_cvt_pk_bf16_f32 v119, v194, v195
	v_cvt_pk_bf16_f32 v131, v196, v197
	v_cvt_pk_bf16_f32 v250, v250, v251
	v_cvt_pk_bf16_f32 v251, v252, v253
	ds_write_b64 v104, v[250:251] offset:8320
	v_mfma_f32_16x16x16_bf16 v[242:245], v[172:173], v[88:89], 0
	v_and_b32_e32 v200, 0xffff0000, v232
	ds_write_b32 v103, v119 offset:12688
	v_and_b32_e32 v201, 0xffff0000, v236
	ds_write_b32 v103, v131 offset:16224
	v_cvt_pk_bf16_f32 v238, v238, v239
	v_cvt_pk_bf16_f32 v239, v240, v241
	ds_write_b64 v104, v[238:239] offset:3840
	v_mfma_f32_16x16x16_bf16 v[246:249], v[116:117], v[74:75], 0
	v_pk_fma_f32 v[198:199], v[150:151], v[194:195], v[198:199]
	v_pk_fma_f32 v[200:201], v[152:153], v[196:197], v[200:201]
	v_and_b32_e32 v202, 0xffff0000, v223
	v_pk_fma_f32 v[194:195], v[16:17], v[194:195], v[198:199] op_sel:[0,1,0] op_sel_hi:[1,0,1]
	v_pk_fma_f32 v[196:197], v[36:37], v[196:197], v[200:201] op_sel:[0,1,0] op_sel_hi:[1,0,1]
	v_cvt_pk_bf16_f32 v242, v242, v243
	v_cvt_pk_bf16_f32 v243, v244, v245
	ds_write_b64 v104, v[242:243] offset:8960
	v_mfma_f32_16x16x16_bf16 v[250:253], v[172:173], v[90:91], 0
	v_and_b32_e32 v203, 0xffff0000, v227
	v_cvt_pk_bf16_f32 v121, v194, v195
	v_cvt_pk_bf16_f32 v132, v196, v197
	v_cvt_pk_bf16_f32 v246, v246, v247
	v_cvt_pk_bf16_f32 v247, v248, v249
	ds_write_b64 v104, v[246:247] offset:4480
	v_lshlrev_b32_e32 v204, 16, v232
	ds_write_b32 v103, v121 offset:12960
	v_lshlrev_b32_e32 v205, 16, v236
	ds_write_b32 v103, v132 offset:15952
	v_cvt_pk_bf16_f32 v250, v250, v251
	v_cvt_pk_bf16_f32 v251, v252, v253
	ds_write_b64 v104, v[250:251] offset:9600
	v_pk_fma_f32 v[202:203], v[150:151], v[194:195], v[202:203]
	v_pk_fma_f32 v[204:205], v[152:153], v[196:197], v[204:205]
	v_lshlrev_b32_e32 v198, 16, v224
	v_pk_fma_f32 v[194:195], v[16:17], v[194:195], v[202:203] op_sel:[0,1,0] op_sel_hi:[1,0,1]
	v_pk_fma_f32 v[196:197], v[36:37], v[196:197], v[204:205] op_sel:[0,1,0] op_sel_hi:[1,0,1]
	ds_read_b128 v[206:209], v109
	ds_read_b128 v[210:213], v109 offset:32
	ds_read_b128 v[214:217], v109 offset:5136
	ds_read_b128 v[218:221], v109 offset:5168
	v_lshlrev_b32_e32 v199, 16, v228
	v_cvt_pk_bf16_f32 v127, v194, v195
	v_cvt_pk_bf16_f32 v135, v196, v197
	v_and_b32_e32 v200, 0xffff0000, v231
	ds_write_b32 v103, v127 offset:13232
	v_and_b32_e32 v201, 0xffff0000, v235
	ds_write_b32 v103, v135 offset:15680
	v_pk_fma_f32 v[198:199], v[150:151], v[194:195], v[198:199]
	v_pk_fma_f32 v[200:201], v[152:153], v[196:197], v[200:201]
	v_and_b32_e32 v202, 0xffff0000, v224
	v_pk_fma_f32 v[194:195], v[16:17], v[194:195], v[198:199] op_sel:[0,1,0] op_sel_hi:[1,0,1]
	v_pk_fma_f32 v[196:197], v[36:37], v[196:197], v[200:201] op_sel:[0,1,0] op_sel_hi:[1,0,1]
	v_and_b32_e32 v203, 0xffff0000, v228
	v_cvt_pk_bf16_f32 v114, v194, v195
	v_cvt_pk_bf16_f32 v128, v196, v197
	v_lshlrev_b32_e32 v204, 16, v231
	ds_write_b32 v103, v114 offset:13504
	v_lshlrev_b32_e32 v205, 16, v235
	ds_write_b32 v103, v128 offset:15408
	v_pk_fma_f32 v[202:203], v[150:151], v[194:195], v[202:203]
	v_pk_fma_f32 v[204:205], v[152:153], v[196:197], v[204:205]
	v_lshlrev_b32_e32 v198, 16, v225
	v_pk_fma_f32 v[194:195], v[16:17], v[194:195], v[202:203] op_sel:[0,1,0] op_sel_hi:[1,0,1]
	v_pk_fma_f32 v[196:197], v[36:37], v[196:197], v[204:205] op_sel:[0,1,0] op_sel_hi:[1,0,1]
	v_lshlrev_b32_e32 v199, 16, v229
	v_cvt_pk_bf16_f32 v119, v194, v195
	v_cvt_pk_bf16_f32 v131, v196, v197
	v_and_b32_e32 v200, 0xffff0000, v230
	ds_write_b32 v103, v119 offset:13776
	v_and_b32_e32 v201, 0xffff0000, v234
	ds_write_b32 v103, v131 offset:15136
	v_pk_fma_f32 v[198:199], v[150:151], v[194:195], v[198:199]
	v_pk_fma_f32 v[200:201], v[152:153], v[196:197], v[200:201]
	v_and_b32_e32 v202, 0xffff0000, v225
	v_pk_fma_f32 v[194:195], v[16:17], v[194:195], v[198:199] op_sel:[0,1,0] op_sel_hi:[1,0,1]
	v_pk_fma_f32 v[196:197], v[36:37], v[196:197], v[200:201] op_sel:[0,1,0] op_sel_hi:[1,0,1]
	v_and_b32_e32 v203, 0xffff0000, v229
	v_cvt_pk_bf16_f32 v121, v194, v195
	v_cvt_pk_bf16_f32 v132, v196, v197
	v_lshlrev_b32_e32 v204, 16, v230
	ds_write_b32 v103, v121 offset:14048
	v_lshlrev_b32_e32 v205, 16, v234
	ds_write_b32 v103, v132 offset:14864
	v_pk_fma_f32 v[202:203], v[150:151], v[194:195], v[202:203]
	v_pk_fma_f32 v[204:205], v[152:153], v[196:197], v[204:205]
	s_waitcnt lgkmcnt(11)
; #define LAS __attribute__((address_space(3)))
; __device__ __forceinline__ unsigned pk2(float lo, float hi) { f32x2 v = {lo, hi}; nbf2 r = __builtin_convertvector(v, nbf2); return __builtin_bit_cast(unsigned, r); }
; #define WAVE_LDS_FENCE() asm volatile("s_waitcnt lgkmcnt(0)" ::: "memory")
; __device__ __forceinline__ float bf_at(const u32x4& lo, const u32x4& hi, int r) { const unsigned w = (r < 8 ? lo : hi)[(r & 7) >> 1]; return (r & 1) ? bf_hi(w) : bf_lo(w); }
; __device__ __forceinline__ void s5_out_phase(LAS unsigned char* lds, const bf16_t* UZ, const unsigned char* ws, const float* dskip, bf16_t* YG) {
;     ...
;             for (int rr = 0; rr < 16; ++rr) {
;                 const int r = rr, rb = 15 - rr;
;                 { const f32x2 bb = {bf_at(fre0, fre1, r), bf_at(fim0, fim1, r)};
;                   const f32x2 n2 = cmac((f32x2){xfr, xfi}, (f32x2){ap[0].x, ap[0].x}, (f32x2){-ap[0].y, ap[0].y}, bb); xfr = n2.x; xfi = n2.y;
;                   *(LAS unsigned*)(xf + r * XB_PITCH + lane * 4) = pk2(n2.x, n2.y); }
;                 { const f32x2 bb = {bf_at(bre0, bre1, rb), bf_at(bim0, bim1, rb)};
;                   const f32x2 n2 = cmac((f32x2){xbr, xbi}, (f32x2){ap[1].x, ap[1].x}, (f32x2){-ap[1].y, ap[1].y}, bb); xbr = n2.x; xbi = n2.y;
;                   *(LAS unsigned*)(xbk + rb * XB_PITCH + lane * 4) = pk2(n2.x, n2.y); }
;             }
;             WAVE_LDS_FENCE();
; #pragma unroll
;             for (int ks = 0; ks < 4; ++ks) {
;                 const bf16x8 Xf = *(const LAS bf16x8*)(xf + fr * XB_PITCH + (8 * fq + 32 * ks) * 2);
;                 const bf16x8 Xb = *(const LAS bf16x8*)(xbk + fr * XB_PITCH + (8 * fq + 32 * ks) * 2);
;                 accY[mf] = __builtin_amdgcn_mfma_f32_16x16x32_bf16(Cf[0][ks], Xf, accY[mf], 0, 0, 0);
;                 accY[mb] = __builtin_amdgcn_mfma_f32_16x16x32_bf16(Cf[1][ks], Xb, accY[mb], 0, 0, 0);
;             }
	v_lshlrev_b32_e32 v198, 16, v206
	v_pk_fma_f32 v[194:195], v[16:17], v[194:195], v[202:203] op_sel:[0,1,0] op_sel_hi:[1,0,1]
	v_pk_fma_f32 v[196:197], v[36:37], v[196:197], v[204:205] op_sel:[0,1,0] op_sel_hi:[1,0,1]
	s_waitcnt lgkmcnt(10)
	v_lshlrev_b32_e32 v199, 16, v210
	v_cvt_pk_bf16_f32 v127, v194, v195
	v_cvt_pk_bf16_f32 v135, v196, v197
	s_waitcnt lgkmcnt(9)
	v_and_b32_e32 v200, 0xffff0000, v217
	ds_write_b32 v103, v127 offset:14320
	s_waitcnt lgkmcnt(9)
	v_and_b32_e32 v201, 0xffff0000, v221
	ds_write_b32 v103, v135 offset:14592
	ds_read_b128 v[222:225], v110 offset:10240
	ds_read_b128 v[226:229], v110 offset:10304
	ds_read_b128 v[230:233], v110 offset:10368
	ds_read_b128 v[234:237], v110 offset:10432
	ds_read_b128 v[238:241], v110 offset:14592
	ds_read_b128 v[242:245], v110 offset:14656
	ds_read_b128 v[246:249], v110 offset:14720
	ds_read_b128 v[250:253], v110 offset:14784
	v_pk_fma_f32 v[198:199], v[150:151], v[194:195], v[198:199]
	v_pk_fma_f32 v[200:201], v[152:153], v[196:197], v[200:201]
	v_and_b32_e32 v202, 0xffff0000, v206
	v_pk_fma_f32 v[194:195], v[16:17], v[194:195], v[198:199] op_sel:[0,1,0] op_sel_hi:[1,0,1]
	v_pk_fma_f32 v[196:197], v[36:37], v[196:197], v[200:201] op_sel:[0,1,0] op_sel_hi:[1,0,1]
	v_and_b32_e32 v203, 0xffff0000, v210
	v_cvt_pk_bf16_f32 v114, v194, v195
	v_cvt_pk_bf16_f32 v128, v196, v197
	v_lshlrev_b32_e32 v204, 16, v217
	ds_write_b32 v103, v114 offset:10240
	v_lshlrev_b32_e32 v205, 16, v221
	ds_write_b32 v103, v128 offset:18672
	v_pk_fma_f32 v[202:203], v[150:151], v[194:195], v[202:203]
	v_pk_fma_f32 v[204:205], v[152:153], v[196:197], v[204:205]
	v_lshlrev_b32_e32 v198, 16, v207
	v_pk_fma_f32 v[194:195], v[16:17], v[194:195], v[202:203] op_sel:[0,1,0] op_sel_hi:[1,0,1]
	v_pk_fma_f32 v[196:197], v[36:37], v[196:197], v[204:205] op_sel:[0,1,0] op_sel_hi:[1,0,1]
	v_lshlrev_b32_e32 v199, 16, v211
	v_cvt_pk_bf16_f32 v119, v194, v195
	v_cvt_pk_bf16_f32 v131, v196, v197
	v_and_b32_e32 v200, 0xffff0000, v216
	ds_write_b32 v103, v119 offset:10512
	v_and_b32_e32 v201, 0xffff0000, v220
	ds_write_b32 v103, v131 offset:18400
	v_pk_fma_f32 v[198:199], v[150:151], v[194:195], v[198:199]
	v_pk_fma_f32 v[200:201], v[152:153], v[196:197], v[200:201]
	v_and_b32_e32 v202, 0xffff0000, v207
	v_pk_fma_f32 v[194:195], v[16:17], v[194:195], v[198:199] op_sel:[0,1,0] op_sel_hi:[1,0,1]
	v_pk_fma_f32 v[196:197], v[36:37], v[196:197], v[200:201] op_sel:[0,1,0] op_sel_hi:[1,0,1]
	s_waitcnt lgkmcnt(11)
	v_mfma_f32_16x16x32_bf16 v[52:55], v[0:3], v[222:225], v[52:55]
	v_and_b32_e32 v203, 0xffff0000, v211
	v_cvt_pk_bf16_f32 v121, v194, v195
	v_cvt_pk_bf16_f32 v132, v196, v197
	s_waitcnt lgkmcnt(7)
	v_mfma_f32_16x16x32_bf16 v[56:59], v[20:23], v[238:241], v[56:59]
	v_lshlrev_b32_e32 v204, 16, v216
	ds_write_b32 v103, v121 offset:10784
	v_lshlrev_b32_e32 v205, 16, v220
	ds_write_b32 v103, v132 offset:18128
	v_mfma_f32_16x16x32_bf16 v[52:55], v[4:7], v[226:229], v[52:55]
	v_pk_fma_f32 v[202:203], v[150:151], v[194:195], v[202:203]
	v_pk_fma_f32 v[204:205], v[152:153], v[196:197], v[204:205]
	v_lshlrev_b32_e32 v198, 16, v208
	v_pk_fma_f32 v[194:195], v[16:17], v[194:195], v[202:203] op_sel:[0,1,0] op_sel_hi:[1,0,1]
	v_pk_fma_f32 v[196:197], v[36:37], v[196:197], v[204:205] op_sel:[0,1,0] op_sel_hi:[1,0,1]
	s_waitcnt lgkmcnt(8)
	v_mfma_f32_16x16x32_bf16 v[56:59], v[24:27], v[242:245], v[56:59]
	v_lshlrev_b32_e32 v199, 16, v212
	v_cvt_pk_bf16_f32 v127, v194, v195
	v_cvt_pk_bf16_f32 v135, v196, v197
	v_mfma_f32_16x16x32_bf16 v[52:55], v[8:11], v[230:233], v[52:55]
	v_and_b32_e32 v200, 0xffff0000, v215
	ds_write_b32 v103, v127 offset:11056
	v_and_b32_e32 v201, 0xffff0000, v219
	ds_write_b32 v103, v135 offset:17856
	s_waitcnt lgkmcnt(9)
	v_mfma_f32_16x16x32_bf16 v[56:59], v[28:31], v[246:249], v[56:59]
	v_pk_fma_f32 v[198:199], v[150:151], v[194:195], v[198:199]
	v_pk_fma_f32 v[200:201], v[152:153], v[196:197], v[200:201]
	v_and_b32_e32 v202, 0xffff0000, v208
	v_pk_fma_f32 v[194:195], v[16:17], v[194:195], v[198:199] op_sel:[0,1,0] op_sel_hi:[1,0,1]
	v_pk_fma_f32 v[196:197], v[36:37], v[196:197], v[200:201] op_sel:[0,1,0] op_sel_hi:[1,0,1]
	v_mfma_f32_16x16x32_bf16 v[52:55], v[12:15], v[234:237], v[52:55]
	v_and_b32_e32 v203, 0xffff0000, v212
	v_cvt_pk_bf16_f32 v114, v194, v195
	v_cvt_pk_bf16_f32 v128, v196, v197
	s_waitcnt lgkmcnt(8)
	v_mfma_f32_16x16x32_bf16 v[56:59], v[32:35], v[250:253], v[56:59]
	v_lshlrev_b32_e32 v204, 16, v215
	ds_write_b32 v103, v114 offset:11328
	v_lshlrev_b32_e32 v205, 16, v219
	ds_write_b32 v103, v128 offset:17584
	ds_read_b128 v[222:225], v109 offset:16
	ds_read_b128 v[226:229], v109 offset:48
	ds_read_b128 v[230:233], v109 offset:5120
	ds_read_b128 v[234:237], v109 offset:5152
	v_pk_fma_f32 v[202:203], v[150:151], v[194:195], v[202:203]
	v_pk_fma_f32 v[204:205], v[152:153], v[196:197], v[204:205]
	v_lshlrev_b32_e32 v198, 16, v209
	v_pk_fma_f32 v[194:195], v[16:17], v[194:195], v[202:203] op_sel:[0,1,0] op_sel_hi:[1,0,1]
	v_pk_fma_f32 v[196:197], v[36:37], v[196:197], v[204:205] op_sel:[0,1,0] op_sel_hi:[1,0,1]
	v_lshlrev_b32_e32 v199, 16, v213
	v_cvt_pk_bf16_f32 v119, v194, v195
	v_cvt_pk_bf16_f32 v131, v196, v197
	v_and_b32_e32 v200, 0xffff0000, v214
	ds_write_b32 v103, v119 offset:11600
	v_and_b32_e32 v201, 0xffff0000, v218
	ds_write_b32 v103, v131 offset:17312
	v_pk_fma_f32 v[198:199], v[150:151], v[194:195], v[198:199]
	v_pk_fma_f32 v[200:201], v[152:153], v[196:197], v[200:201]
	v_and_b32_e32 v202, 0xffff0000, v209
	v_pk_fma_f32 v[194:195], v[16:17], v[194:195], v[198:199] op_sel:[0,1,0] op_sel_hi:[1,0,1]
	v_pk_fma_f32 v[196:197], v[36:37], v[196:197], v[200:201] op_sel:[0,1,0] op_sel_hi:[1,0,1]
	v_and_b32_e32 v203, 0xffff0000, v213
	v_cvt_pk_bf16_f32 v121, v194, v195
	v_cvt_pk_bf16_f32 v132, v196, v197
	v_lshlrev_b32_e32 v204, 16, v214
	ds_write_b32 v103, v121 offset:11872
	v_lshlrev_b32_e32 v205, 16, v218
	ds_write_b32 v103, v132 offset:17040
	v_pk_fma_f32 v[202:203], v[150:151], v[194:195], v[202:203]
	v_pk_fma_f32 v[204:205], v[152:153], v[196:197], v[204:205]
	s_waitcnt lgkmcnt(7)
; #define LAS __attribute__((address_space(3)))
; __device__ __forceinline__ unsigned pk2(float lo, float hi) { f32x2 v = {lo, hi}; nbf2 r = __builtin_convertvector(v, nbf2); return __builtin_bit_cast(unsigned, r); }
; #define WAVE_LDS_FENCE() asm volatile("s_waitcnt lgkmcnt(0)" ::: "memory")
; __device__ __forceinline__ float bf_at(const u32x4& lo, const u32x4& hi, int r) { const unsigned w = (r < 8 ? lo : hi)[(r & 7) >> 1]; return (r & 1) ? bf_hi(w) : bf_lo(w); }
; __device__ __forceinline__ void s5_out_phase(LAS unsigned char* lds, const bf16_t* UZ, const unsigned char* ws, const float* dskip, bf16_t* YG) {
;     ...
;             for (int rr = 0; rr < 16; ++rr) {
;                 const int r = rr, rb = 15 - rr;
;                 { const f32x2 bb = {bf_at(fre0, fre1, r), bf_at(fim0, fim1, r)};
;                   const f32x2 n2 = cmac((f32x2){xfr, xfi}, (f32x2){ap[0].x, ap[0].x}, (f32x2){-ap[0].y, ap[0].y}, bb); xfr = n2.x; xfi = n2.y;
;                   *(LAS unsigned*)(xf + r * XB_PITCH + lane * 4) = pk2(n2.x, n2.y); }
;                 { const f32x2 bb = {bf_at(bre0, bre1, rb), bf_at(bim0, bim1, rb)};
;                   const f32x2 n2 = cmac((f32x2){xbr, xbi}, (f32x2){ap[1].x, ap[1].x}, (f32x2){-ap[1].y, ap[1].y}, bb); xbr = n2.x; xbi = n2.y;
;                   *(LAS unsigned*)(xbk + rb * XB_PITCH + lane * 4) = pk2(n2.x, n2.y); }
;             }
;             WAVE_LDS_FENCE();
; #pragma unroll
;             for (int ks = 0; ks < 4; ++ks) {
;                 const bf16x8 Xf = *(const LAS bf16x8*)(xf + fr * XB_PITCH + (8 * fq + 32 * ks) * 2);
;                 const bf16x8 Xb = *(const LAS bf16x8*)(xbk + fr * XB_PITCH + (8 * fq + 32 * ks) * 2);
;                 accY[mf] = __builtin_amdgcn_mfma_f32_16x16x32_bf16(Cf[0][ks], Xf, accY[mf], 0, 0, 0);
;                 accY[mb] = __builtin_amdgcn_mfma_f32_16x16x32_bf16(Cf[1][ks], Xb, accY[mb], 0, 0, 0);
;             }
	v_lshlrev_b32_e32 v198, 16, v222
	v_pk_fma_f32 v[194:195], v[16:17], v[194:195], v[202:203] op_sel:[0,1,0] op_sel_hi:[1,0,1]
	v_pk_fma_f32 v[196:197], v[36:37], v[196:197], v[204:205] op_sel:[0,1,0] op_sel_hi:[1,0,1]
	s_waitcnt lgkmcnt(6)
	v_lshlrev_b32_e32 v199, 16, v226
	v_cvt_pk_bf16_f32 v127, v194, v195
	v_cvt_pk_bf16_f32 v135, v196, v197
	s_waitcnt lgkmcnt(5)
	v_and_b32_e32 v200, 0xffff0000, v233
	ds_write_b32 v103, v127 offset:12144
	s_waitcnt lgkmcnt(5)
	v_and_b32_e32 v201, 0xffff0000, v237
	ds_write_b32 v103, v135 offset:16768
	v_pk_fma_f32 v[198:199], v[150:151], v[194:195], v[198:199]
	v_pk_fma_f32 v[200:201], v[152:153], v[196:197], v[200:201]
	v_and_b32_e32 v202, 0xffff0000, v222
	v_pk_fma_f32 v[194:195], v[16:17], v[194:195], v[198:199] op_sel:[0,1,0] op_sel_hi:[1,0,1]
	v_pk_fma_f32 v[196:197], v[36:37], v[196:197], v[200:201] op_sel:[0,1,0] op_sel_hi:[1,0,1]
	v_and_b32_e32 v203, 0xffff0000, v226
	v_cvt_pk_bf16_f32 v114, v194, v195
	v_cvt_pk_bf16_f32 v128, v196, v197
	v_lshlrev_b32_e32 v204, 16, v233
	ds_write_b32 v103, v114 offset:12416
	v_lshlrev_b32_e32 v205, 16, v237
	ds_write_b32 v103, v128 offset:16496
	v_pk_fma_f32 v[202:203], v[150:151], v[194:195], v[202:203]
	v_pk_fma_f32 v[204:205], v[152:153], v[196:197], v[204:205]
	v_lshlrev_b32_e32 v198, 16, v223
	v_pk_fma_f32 v[194:195], v[16:17], v[194:195], v[202:203] op_sel:[0,1,0] op_sel_hi:[1,0,1]
	v_pk_fma_f32 v[196:197], v[36:37], v[196:197], v[204:205] op_sel:[0,1,0] op_sel_hi:[1,0,1]
	v_lshlrev_b32_e32 v199, 16, v227
	v_cvt_pk_bf16_f32 v119, v194, v195
	v_cvt_pk_bf16_f32 v131, v196, v197
	v_and_b32_e32 v200, 0xffff0000, v232
	ds_write_b32 v103, v119 offset:12688
	v_and_b32_e32 v201, 0xffff0000, v236
	ds_write_b32 v103, v131 offset:16224
	v_pk_fma_f32 v[198:199], v[150:151], v[194:195], v[198:199]
	v_pk_fma_f32 v[200:201], v[152:153], v[196:197], v[200:201]
	v_and_b32_e32 v202, 0xffff0000, v223
	v_pk_fma_f32 v[194:195], v[16:17], v[194:195], v[198:199] op_sel:[0,1,0] op_sel_hi:[1,0,1]
	v_pk_fma_f32 v[196:197], v[36:37], v[196:197], v[200:201] op_sel:[0,1,0] op_sel_hi:[1,0,1]
	v_and_b32_e32 v203, 0xffff0000, v227
	v_cvt_pk_bf16_f32 v121, v194, v195
	v_cvt_pk_bf16_f32 v132, v196, v197
	v_lshlrev_b32_e32 v204, 16, v232
	ds_write_b32 v103, v121 offset:12960
	v_lshlrev_b32_e32 v205, 16, v236
	ds_write_b32 v103, v132 offset:15952
	v_pk_fma_f32 v[202:203], v[150:151], v[194:195], v[202:203]
	v_pk_fma_f32 v[204:205], v[152:153], v[196:197], v[204:205]
	v_lshlrev_b32_e32 v198, 16, v224
	v_pk_fma_f32 v[194:195], v[16:17], v[194:195], v[202:203] op_sel:[0,1,0] op_sel_hi:[1,0,1]
	v_pk_fma_f32 v[196:197], v[36:37], v[196:197], v[204:205] op_sel:[0,1,0] op_sel_hi:[1,0,1]
	v_lshlrev_b32_e32 v199, 16, v228
	v_cvt_pk_bf16_f32 v127, v194, v195
	v_cvt_pk_bf16_f32 v135, v196, v197
	v_and_b32_e32 v200, 0xffff0000, v231
	ds_write_b32 v103, v127 offset:13232
	v_and_b32_e32 v201, 0xffff0000, v235
	ds_write_b32 v103, v135 offset:15680
	v_pk_fma_f32 v[198:199], v[150:151], v[194:195], v[198:199]
	v_pk_fma_f32 v[200:201], v[152:153], v[196:197], v[200:201]
	v_and_b32_e32 v202, 0xffff0000, v224
	v_pk_fma_f32 v[194:195], v[16:17], v[194:195], v[198:199] op_sel:[0,1,0] op_sel_hi:[1,0,1]
	v_pk_fma_f32 v[196:197], v[36:37], v[196:197], v[200:201] op_sel:[0,1,0] op_sel_hi:[1,0,1]
	v_and_b32_e32 v203, 0xffff0000, v228
	v_cvt_pk_bf16_f32 v114, v194, v195
	v_cvt_pk_bf16_f32 v128, v196, v197
	v_lshlrev_b32_e32 v204, 16, v231
	ds_write_b32 v103, v114 offset:13504
	v_lshlrev_b32_e32 v205, 16, v235
	ds_write_b32 v103, v128 offset:15408
	v_pk_fma_f32 v[202:203], v[150:151], v[194:195], v[202:203]
	v_pk_fma_f32 v[204:205], v[152:153], v[196:197], v[204:205]
	v_lshlrev_b32_e32 v198, 16, v225
	v_pk_fma_f32 v[194:195], v[16:17], v[194:195], v[202:203] op_sel:[0,1,0] op_sel_hi:[1,0,1]
	v_pk_fma_f32 v[196:197], v[36:37], v[196:197], v[204:205] op_sel:[0,1,0] op_sel_hi:[1,0,1]
	v_lshlrev_b32_e32 v199, 16, v229
	v_cvt_pk_bf16_f32 v119, v194, v195
	v_cvt_pk_bf16_f32 v131, v196, v197
	v_and_b32_e32 v200, 0xffff0000, v230
	ds_write_b32 v103, v119 offset:13776
	v_and_b32_e32 v201, 0xffff0000, v234
	ds_write_b32 v103, v131 offset:15136
	v_pk_fma_f32 v[198:199], v[150:151], v[194:195], v[198:199]
	v_pk_fma_f32 v[200:201], v[152:153], v[196:197], v[200:201]
	v_and_b32_e32 v202, 0xffff0000, v225
	v_pk_fma_f32 v[194:195], v[16:17], v[194:195], v[198:199] op_sel:[0,1,0] op_sel_hi:[1,0,1]
	v_pk_fma_f32 v[196:197], v[36:37], v[196:197], v[200:201] op_sel:[0,1,0] op_sel_hi:[1,0,1]
	v_and_b32_e32 v203, 0xffff0000, v229
	v_cvt_pk_bf16_f32 v121, v194, v195
	v_cvt_pk_bf16_f32 v132, v196, v197
	v_lshlrev_b32_e32 v204, 16, v230
	ds_write_b32 v103, v121 offset:14048
	v_lshlrev_b32_e32 v205, 16, v234
	ds_write_b32 v103, v132 offset:14864
	v_pk_fma_f32 v[202:203], v[150:151], v[194:195], v[202:203]
	v_pk_fma_f32 v[204:205], v[152:153], v[196:197], v[204:205]
	v_pk_fma_f32 v[194:195], v[16:17], v[194:195], v[202:203] op_sel:[0,1,0] op_sel_hi:[1,0,1]
	v_pk_fma_f32 v[196:197], v[36:37], v[196:197], v[204:205] op_sel:[0,1,0] op_sel_hi:[1,0,1]
	v_cvt_pk_bf16_f32 v127, v194, v195
	v_cvt_pk_bf16_f32 v135, v196, v197
	ds_write_b32 v103, v127 offset:14320
	ds_write_b32 v103, v135 offset:14592
	ds_read_b128 v[222:225], v110 offset:10240
	ds_read_b128 v[226:229], v110 offset:10304
	ds_read_b128 v[230:233], v110 offset:10368
	ds_read_b128 v[234:237], v110 offset:10432
	ds_read_b128 v[238:241], v110 offset:14592
	ds_read_b128 v[242:245], v110 offset:14656
	ds_read_b128 v[246:249], v110 offset:14720
	ds_read_b128 v[250:253], v110 offset:14784
	s_waitcnt lgkmcnt(7)
	v_mfma_f32_16x16x32_bf16 v[44:47], v[0:3], v[222:225], v[44:47]
	s_waitcnt lgkmcnt(3)
; #define LAS __attribute__((address_space(3)))
; __device__ __forceinline__ unsigned pk2(float lo, float hi) { f32x2 v = {lo, hi}; nbf2 r = __builtin_convertvector(v, nbf2); return __builtin_bit_cast(unsigned, r); }
; __device__ __forceinline__ float bf_lo(unsigned w) { return __uint_as_float(w << 16); }
; __device__ __forceinline__ float bf_hi(unsigned w) { return __uint_as_float(w & 0xffff0000u); }
; __device__ __forceinline__ float fast_rcp(float x) { return __builtin_amdgcn_rcpf(x); }
; __device__ __forceinline__ float fast_exp2(float x) { return __builtin_amdgcn_exp2f(x); }
; __device__ __forceinline__ float gelu_f(float v) {
;     const float av = fabsf(v), d = av * 0.2316418882f + 1.0f;
;     const float t = fast_rcp(d);
;     float q = t * 0.5307027145f + (-0.7265760135f); q = q * t + 0.7107068705f; q = q * t + (-0.142248368f); q = q * t + 0.127414796f; q = q * t;
;     const float e = fast_exp2((v * v) * (-0.72134752044f));
;     const float m = v * (q * e), r = v - m;
;     return v < 0.f ? m : r;
; }
; __device__ __forceinline__ void s5_out_phase(LAS unsigned char* lds, const bf16_t* UZ, const unsigned char* ws, const float* dskip, bf16_t* YG) {
;     ...
;             for (int ks = 0; ks < 4; ++ks) {
;                 const bf16x8 Xf = *(const LAS bf16x8*)(xf + fr * XB_PITCH + (8 * fq + 32 * ks) * 2);
;                 const bf16x8 Xb = *(const LAS bf16x8*)(xbk + fr * XB_PITCH + (8 * fq + 32 * ks) * 2);
;                 accY[mf] = __builtin_amdgcn_mfma_f32_16x16x32_bf16(Cf[0][ks], Xf, accY[mf], 0, 0, 0);
;                 accY[mb] = __builtin_amdgcn_mfma_f32_16x16x32_bf16(Cf[1][ks], Xb, accY[mb], 0, 0, 0);
;             }
;         }
; #pragma unroll
;         for (int m = 0; m < 4; ++m) {
;             const unsigned u0 = (unsigned)(unsigned short)Uf[m][0] | ((unsigned)(unsigned short)Uf[m][1] << 16), u1 = (unsigned)(unsigned short)Uf[m][2] | ((unsigned)(unsigned short)Uf[m][3] << 16);
;             const float y0 = gelu_f(accY[m][0] + dsk[0] * bf_lo(u0)), y1 = gelu_f(accY[m][1] + dsk[1] * bf_hi(u0));
;             const float y2 = gelu_f(accY[m][2] + dsk[2] * bf_lo(u1)), y3 = gelu_f(accY[m][3] + dsk[3] * bf_hi(u1));
;             u32x2 w; w.x = pk2(y0, y1); w.y = pk2(y2, y3);
;             *(u32x2*)(YG + (size_t)(rowbase + 16 * m + fr) * D + 16 * g + 4 * fq) = w;
;         }
	v_mfma_f32_16x16x32_bf16 v[48:51], v[20:23], v[238:241], v[48:51]
	v_mfma_f32_16x16x32_bf16 v[44:47], v[4:7], v[226:229], v[44:47]
	s_waitcnt lgkmcnt(2)
	v_mfma_f32_16x16x32_bf16 v[48:51], v[24:27], v[242:245], v[48:51]
	v_mfma_f32_16x16x32_bf16 v[44:47], v[8:11], v[230:233], v[44:47]
	s_waitcnt lgkmcnt(1)
	v_mfma_f32_16x16x32_bf16 v[48:51], v[28:31], v[246:249], v[48:51]
	v_mfma_f32_16x16x32_bf16 v[44:47], v[12:15], v[234:237], v[44:47]
	s_waitcnt lgkmcnt(0)
	v_mfma_f32_16x16x32_bf16 v[48:51], v[32:35], v[250:253], v[48:51]
	v_ashrrev_i32_e32 v167, 31, v166
	s_nop 7
	s_nop 4
	v_lshlrev_b32_e32 v188, 16, v172
	v_and_b32_e32 v189, 0xffff0000, v172
	s_waitcnt vmcnt(0)
	v_pk_fma_f32 v[188:189], v[40:41], v[188:189], v[48:49]
	v_lshlrev_b32_e32 v172, 16, v173
	v_fma_f32 v48, |v188|, s21, 1.0
	v_rcp_f32_e32 v190, v48
	v_fma_f32 v48, |v189|, s21, 1.0
	v_rcp_f32_e32 v191, v48
	v_pk_mul_f32 v[194:195], v[188:189], v[188:189]
	v_and_b32_e32 v173, 0xffff0000, v173
	v_mul_f32_e32 v48, 0xbf38aa3b, v194
	v_exp_f32_e32 v194, v48
	v_mov_b64_e32 v[48:49], s[4:5]
	v_pk_fma_f32 v[196:197], v[190:191], s[2:3], v[48:49] op_sel_hi:[1,0,0]
	v_mul_f32_e32 v114, 0xbf38aa3b, v195
	v_pk_fma_f32 v[196:197], v[190:191], v[196:197], s[8:9] op_sel_hi:[1,1,0]
	v_exp_f32_e32 v195, v114
	v_pk_fma_f32 v[196:197], v[190:191], v[196:197], s[20:21] op_sel_hi:[1,1,0]
	v_pk_fma_f32 v[50:51], v[42:43], v[172:173], v[50:51]
	v_pk_fma_f32 v[196:197], v[190:191], v[196:197], s[22:23] op_sel_hi:[1,1,0]
	v_fma_f32 v121, |v50|, s21, 1.0
	v_pk_mul_f32 v[190:191], v[190:191], v[196:197]
	v_rcp_f32_e32 v172, v121
	v_fma_f32 v121, |v51|, s21, 1.0
	v_pk_mul_f32 v[190:191], v[194:195], v[190:191]
	v_rcp_f32_e32 v173, v121
	v_pk_mul_f32 v[194:195], v[188:189], v[190:191]
	v_pk_fma_f32 v[190:191], v[188:189], v[190:191], v[188:189] neg_lo:[1,0,0] neg_hi:[1,0,0]
	v_cmp_gt_f32_e32 vcc, 0, v189
	s_nop 1
	v_cndmask_b32_e32 v114, v191, v195, vcc
	v_cmp_gt_f32_e32 vcc, 0, v188
	v_pk_mul_f32 v[188:189], v[50:51], v[50:51]
	s_nop 0
	v_mul_f32_e32 v121, 0xbf38aa3b, v188
	v_cndmask_b32_e32 v119, v190, v194, vcc
	v_exp_f32_e32 v188, v121
	v_pk_fma_f32 v[190:191], v[172:173], s[2:3], v[48:49] op_sel_hi:[1,0,0]
	v_mul_f32_e32 v121, 0xbf38aa3b, v189
	v_pk_fma_f32 v[190:191], v[172:173], v[190:191], s[8:9] op_sel_hi:[1,1,0]
	v_exp_f32_e32 v189, v121
	v_pk_fma_f32 v[190:191], v[172:173], v[190:191], s[20:21] op_sel_hi:[1,1,0]
	v_cmp_gt_f32_e32 vcc, 0, v51
	v_pk_fma_f32 v[190:191], v[172:173], v[190:191], s[22:23] op_sel_hi:[1,1,0]
	s_nop 0
	v_pk_mul_f32 v[172:173], v[172:173], v[190:191]
	s_nop 0
	v_pk_mul_f32 v[172:173], v[188:189], v[172:173]
	s_nop 0
	v_pk_mul_f32 v[188:189], v[50:51], v[172:173]
	v_pk_fma_f32 v[172:173], v[50:51], v[172:173], v[50:51] neg_lo:[1,0,0] neg_hi:[1,0,0]
	s_nop 0
	v_cndmask_b32_e32 v51, v173, v189, vcc
	v_cmp_gt_f32_e32 vcc, 0, v50
	v_cvt_pk_bf16_f32 v50, v119, v114
	s_nop 0
	v_cndmask_b32_e32 v121, v172, v188, vcc
	v_lshlrev_b64 v[172:173], 11, v[166:167]
	v_cvt_pk_bf16_f32 v51, v121, v51
	v_lshl_add_u64 v[172:173], v[154:155], 0, v[172:173]
	global_store_dwordx2 v[172:173], v[50:51], off
	v_lshlrev_b32_e32 v50, 16, v170
	v_and_b32_e32 v51, 0xffff0000, v170
	v_pk_fma_f32 v[50:51], v[40:41], v[50:51], v[56:57]
	s_nop 0
	v_fma_f32 v56, |v50|, s21, 1.0
	v_fma_f32 v57, |v51|, s21, 1.0
	v_rcp_f32_e32 v56, v56
	v_rcp_f32_e32 v57, v57
	v_pk_mul_f32 v[172:173], v[50:51], v[50:51]
	v_cmp_gt_f32_e32 vcc, 0, v51
	v_mul_f32_e32 v114, 0xbf38aa3b, v172
	v_exp_f32_e32 v172, v114
	v_pk_fma_f32 v[188:189], v[56:57], s[2:3], v[48:49] op_sel_hi:[1,0,0]
	v_mul_f32_e32 v114, 0xbf38aa3b, v173
	v_pk_fma_f32 v[188:189], v[56:57], v[188:189], s[8:9] op_sel_hi:[1,1,0]
	v_exp_f32_e32 v173, v114
	v_pk_fma_f32 v[188:189], v[56:57], v[188:189], s[20:21] op_sel_hi:[1,1,0]
	s_nop 0
	v_pk_fma_f32 v[188:189], v[56:57], v[188:189], s[22:23] op_sel_hi:[1,1,0]
	s_nop 0
	v_pk_mul_f32 v[56:57], v[56:57], v[188:189]
	s_nop 0
	v_pk_mul_f32 v[56:57], v[172:173], v[56:57]
	s_nop 0
	v_pk_mul_f32 v[172:173], v[50:51], v[56:57]
	v_pk_fma_f32 v[56:57], v[50:51], v[56:57], v[50:51] neg_lo:[1,0,0] neg_hi:[1,0,0]
	v_and_b32_e32 v51, 0xffff0000, v171
	v_cndmask_b32_e32 v114, v57, v173, vcc
	v_cmp_gt_f32_e32 vcc, 0, v50
	v_lshlrev_b32_e32 v50, 16, v171
	v_pk_fma_f32 v[50:51], v[42:43], v[50:51], v[58:59]
	v_cndmask_b32_e32 v119, v56, v172, vcc
	v_fma_f32 v56, |v50|, s21, 1.0
	v_fma_f32 v57, |v51|, s21, 1.0
	v_rcp_f32_e32 v56, v56
	v_rcp_f32_e32 v57, v57
	v_pk_mul_f32 v[58:59], v[50:51], v[50:51]
	v_cmp_gt_f32_e32 vcc, 0, v51
	v_mul_f32_e32 v58, 0xbf38aa3b, v58
	v_pk_fma_f32 v[170:171], v[56:57], s[2:3], v[48:49] op_sel_hi:[1,0,0]
	v_mul_f32_e32 v59, 0xbf38aa3b, v59
	v_exp_f32_e32 v58, v58
	v_pk_fma_f32 v[170:171], v[56:57], v[170:171], s[8:9] op_sel_hi:[1,1,0]
	v_exp_f32_e32 v59, v59
	v_pk_fma_f32 v[170:171], v[56:57], v[170:171], s[20:21] op_sel_hi:[1,1,0]
	v_mov_b64_e32 v[172:173], v[174:175]
	v_pk_fma_f32 v[170:171], v[56:57], v[170:171], s[22:23] op_sel_hi:[1,1,0]
	s_nop 0
	v_pk_mul_f32 v[56:57], v[56:57], v[170:171]
	v_mov_b64_e32 v[170:171], v[176:177]
	v_pk_mul_f32 v[56:57], v[58:59], v[56:57]
	s_nop 0
	v_pk_mul_f32 v[58:59], v[50:51], v[56:57]
	v_pk_fma_f32 v[56:57], v[50:51], v[56:57], v[50:51] neg_lo:[1,0,0] neg_hi:[1,0,0]
	s_nop 0
	v_cndmask_b32_e32 v51, v57, v59, vcc
; __device__ __forceinline__ unsigned pk2(float lo, float hi) { f32x2 v = {lo, hi}; nbf2 r = __builtin_convertvector(v, nbf2); return __builtin_bit_cast(unsigned, r); }
; __device__ __forceinline__ float bf_lo(unsigned w) { return __uint_as_float(w << 16); }
; __device__ __forceinline__ float bf_hi(unsigned w) { return __uint_as_float(w & 0xffff0000u); }
; __device__ __forceinline__ float fast_rcp(float x) { return __builtin_amdgcn_rcpf(x); }
; __device__ __forceinline__ float fast_exp2(float x) { return __builtin_amdgcn_exp2f(x); }
; __device__ __forceinline__ float gelu_f(float v) {
;     const float av = fabsf(v), d = av * 0.2316418882f + 1.0f;
;     const float t = fast_rcp(d);
;     float q = t * 0.5307027145f + (-0.7265760135f); q = q * t + 0.7107068705f; q = q * t + (-0.142248368f); q = q * t + 0.127414796f; q = q * t;
;     const float e = fast_exp2((v * v) * (-0.72134752044f));
;     const float m = v * (q * e), r = v - m;
;     return v < 0.f ? m : r;
; }
; __device__ __forceinline__ void s5_out_phase(LAS unsigned char* lds, const bf16_t* UZ, const unsigned char* ws, const float* dskip, bf16_t* YG) {
;     ...
; #pragma unroll
;         for (int m = 0; m < 4; ++m) {
;             const unsigned u0 = (unsigned)(unsigned short)Uf[m][0] | ((unsigned)(unsigned short)Uf[m][1] << 16), u1 = (unsigned)(unsigned short)Uf[m][2] | ((unsigned)(unsigned short)Uf[m][3] << 16);
;             const float y0 = gelu_f(accY[m][0] + dsk[0] * bf_lo(u0)), y1 = gelu_f(accY[m][1] + dsk[1] * bf_hi(u0));
;             const float y2 = gelu_f(accY[m][2] + dsk[2] * bf_lo(u1)), y3 = gelu_f(accY[m][3] + dsk[3] * bf_hi(u1));
;             u32x2 w; w.x = pk2(y0, y1); w.y = pk2(y2, y3);
;             *(u32x2*)(YG + (size_t)(rowbase + 16 * m + fr) * D + 16 * g + 4 * fq) = w;
;         }
	v_cmp_gt_f32_e32 vcc, 0, v50
	v_cvt_pk_bf16_f32 v50, v119, v114
	s_nop 0
	v_cndmask_b32_e32 v56, v56, v58, vcc
	v_cvt_pk_bf16_f32 v51, v56, v51
	v_add_u32_e32 v56, 16, v166
	v_ashrrev_i32_e32 v57, 31, v56
	v_lshlrev_b64 v[56:57], 11, v[56:57]
	v_lshl_add_u64 v[56:57], v[154:155], 0, v[56:57]
	global_store_dwordx2 v[56:57], v[50:51], off
	v_lshlrev_b32_e32 v50, 16, v168
	v_and_b32_e32 v51, 0xffff0000, v168
	v_pk_fma_f32 v[50:51], v[40:41], v[50:51], v[52:53]
	s_nop 0
	v_fma_f32 v52, |v50|, s21, 1.0
	v_fma_f32 v53, |v51|, s21, 1.0
	v_rcp_f32_e32 v52, v52
	v_rcp_f32_e32 v53, v53
	v_pk_mul_f32 v[56:57], v[50:51], v[50:51]
	v_cmp_gt_f32_e32 vcc, 0, v51
	v_mul_f32_e32 v56, 0xbf38aa3b, v56
	v_pk_fma_f32 v[58:59], v[52:53], s[2:3], v[48:49] op_sel_hi:[1,0,0]
	v_mul_f32_e32 v57, 0xbf38aa3b, v57
	v_exp_f32_e32 v56, v56
	v_pk_fma_f32 v[58:59], v[52:53], v[58:59], s[8:9] op_sel_hi:[1,1,0]
	v_exp_f32_e32 v57, v57
	v_pk_fma_f32 v[58:59], v[52:53], v[58:59], s[20:21] op_sel_hi:[1,1,0]
	s_nop 0
	v_pk_fma_f32 v[58:59], v[52:53], v[58:59], s[22:23] op_sel_hi:[1,1,0]
	s_nop 0
	v_pk_mul_f32 v[52:53], v[52:53], v[58:59]
	s_nop 0
	v_pk_mul_f32 v[52:53], v[56:57], v[52:53]
	s_nop 0
	v_pk_mul_f32 v[56:57], v[50:51], v[52:53]
	v_pk_fma_f32 v[52:53], v[50:51], v[52:53], v[50:51] neg_lo:[1,0,0] neg_hi:[1,0,0]
	v_and_b32_e32 v51, 0xffff0000, v169
	v_cndmask_b32_e32 v58, v53, v57, vcc
	v_cmp_gt_f32_e32 vcc, 0, v50
	v_lshlrev_b32_e32 v50, 16, v169
	v_pk_fma_f32 v[50:51], v[42:43], v[50:51], v[54:55]
	v_cndmask_b32_e32 v59, v52, v56, vcc
	v_fma_f32 v52, |v50|, s21, 1.0
	v_fma_f32 v53, |v51|, s21, 1.0
	v_rcp_f32_e32 v52, v52
	v_rcp_f32_e32 v53, v53
	v_pk_mul_f32 v[54:55], v[50:51], v[50:51]
	v_cmp_gt_f32_e32 vcc, 0, v51
	v_mul_f32_e32 v54, 0xbf38aa3b, v54
	v_pk_fma_f32 v[56:57], v[52:53], s[2:3], v[48:49] op_sel_hi:[1,0,0]
	v_mul_f32_e32 v55, 0xbf38aa3b, v55
	v_exp_f32_e32 v54, v54
	v_pk_fma_f32 v[56:57], v[52:53], v[56:57], s[8:9] op_sel_hi:[1,1,0]
	v_exp_f32_e32 v55, v55
	v_pk_fma_f32 v[56:57], v[52:53], v[56:57], s[20:21] op_sel_hi:[1,1,0]
	v_mov_b64_e32 v[168:169], v[178:179]
	v_pk_fma_f32 v[56:57], v[52:53], v[56:57], s[22:23] op_sel_hi:[1,1,0]
	s_nop 0
	v_pk_mul_f32 v[52:53], v[52:53], v[56:57]
	s_nop 0
	v_pk_mul_f32 v[52:53], v[54:55], v[52:53]
	s_nop 0
	v_pk_mul_f32 v[54:55], v[50:51], v[52:53]
	v_pk_fma_f32 v[52:53], v[50:51], v[52:53], v[50:51] neg_lo:[1,0,0] neg_hi:[1,0,0]
	s_nop 0
	v_cndmask_b32_e32 v51, v53, v55, vcc
	v_cmp_gt_f32_e32 vcc, 0, v50
	v_cvt_pk_bf16_f32 v50, v59, v58
	s_nop 0
	v_cndmask_b32_e32 v52, v52, v54, vcc
	v_cvt_pk_bf16_f32 v51, v52, v51
	v_add_u32_e32 v52, 32, v166
	v_ashrrev_i32_e32 v53, 31, v52
	v_lshlrev_b64 v[52:53], 11, v[52:53]
	v_lshl_add_u64 v[52:53], v[154:155], 0, v[52:53]
	global_store_dwordx2 v[52:53], v[50:51], off
	v_lshlrev_b32_e32 v50, 16, v116
	v_and_b32_e32 v51, 0xffff0000, v116
	v_pk_fma_f32 v[44:45], v[40:41], v[50:51], v[44:45]
	s_nop 0
	v_fma_f32 v50, |v44|, s21, 1.0
	v_fma_f32 v51, |v45|, s21, 1.0
	v_rcp_f32_e32 v50, v50
	v_rcp_f32_e32 v51, v51
	v_pk_mul_f32 v[52:53], v[44:45], v[44:45]
	v_cmp_gt_f32_e32 vcc, 0, v45
	v_mul_f32_e32 v52, 0xbf38aa3b, v52
	v_pk_fma_f32 v[54:55], v[50:51], s[2:3], v[48:49] op_sel_hi:[1,0,0]
	v_mul_f32_e32 v53, 0xbf38aa3b, v53
	v_exp_f32_e32 v52, v52
	v_pk_fma_f32 v[54:55], v[50:51], v[54:55], s[8:9] op_sel_hi:[1,1,0]
	v_exp_f32_e32 v53, v53
	v_pk_fma_f32 v[54:55], v[50:51], v[54:55], s[20:21] op_sel_hi:[1,1,0]
	s_nop 0
	v_pk_fma_f32 v[54:55], v[50:51], v[54:55], s[22:23] op_sel_hi:[1,1,0]
	s_nop 0
	v_pk_mul_f32 v[50:51], v[50:51], v[54:55]
	s_nop 0
	v_pk_mul_f32 v[50:51], v[52:53], v[50:51]
	s_nop 0
	v_pk_mul_f32 v[52:53], v[44:45], v[50:51]
	v_pk_fma_f32 v[50:51], v[44:45], v[50:51], v[44:45] neg_lo:[1,0,0] neg_hi:[1,0,0]
	v_and_b32_e32 v45, 0xffff0000, v117
	v_cndmask_b32_e32 v53, v51, v53, vcc
	v_cmp_gt_f32_e32 vcc, 0, v44
	v_lshlrev_b32_e32 v44, 16, v117
	v_pk_fma_f32 v[44:45], v[42:43], v[44:45], v[46:47]
	v_cndmask_b32_e32 v52, v50, v52, vcc
	v_fma_f32 v46, |v44|, s21, 1.0
	v_fma_f32 v47, |v45|, s21, 1.0
	v_rcp_f32_e32 v46, v46
	v_rcp_f32_e32 v47, v47
	v_pk_mul_f32 v[50:51], v[44:45], v[44:45]
	v_cmp_gt_f32_e32 vcc, 0, v45
	v_mul_f32_e32 v50, 0xbf38aa3b, v50
	v_pk_fma_f32 v[48:49], v[46:47], s[2:3], v[48:49] op_sel_hi:[1,0,0]
	v_mul_f32_e32 v51, 0xbf38aa3b, v51
	v_exp_f32_e32 v50, v50
	v_pk_fma_f32 v[48:49], v[46:47], v[48:49], s[8:9] op_sel_hi:[1,1,0]
	v_exp_f32_e32 v51, v51
	v_pk_fma_f32 v[48:49], v[46:47], v[48:49], s[20:21] op_sel_hi:[1,1,0]
	v_mov_b64_e32 v[116:117], v[180:181]
	v_pk_fma_f32 v[48:49], v[46:47], v[48:49], s[22:23] op_sel_hi:[1,1,0]
	s_nop 0
	v_pk_mul_f32 v[46:47], v[46:47], v[48:49]
	s_nop 0
	v_pk_mul_f32 v[46:47], v[50:51], v[46:47]
	s_nop 0
	v_pk_mul_f32 v[48:49], v[44:45], v[46:47]
	v_pk_fma_f32 v[46:47], v[44:45], v[46:47], v[44:45] neg_lo:[1,0,0] neg_hi:[1,0,0]
	s_nop 0
	v_cndmask_b32_e32 v45, v47, v49, vcc
	v_cmp_gt_f32_e32 vcc, 0, v44
	v_cvt_pk_bf16_f32 v44, v52, v53
	s_nop 0
	v_cndmask_b32_e32 v46, v46, v48, vcc
	v_cvt_pk_bf16_f32 v45, v46, v45
	v_add_u32_e32 v46, 48, v166
	v_ashrrev_i32_e32 v47, 31, v46
	v_lshlrev_b64 v[46:47], 11, v[46:47]
	v_lshl_add_u64 v[46:47], v[154:155], 0, v[46:47]
	v_add_u32_e32 v166, s3, v166
	s_andn2_b64 vcc, exec, s[24:25]
	global_store_dwordx2 v[46:47], v[44:45], off
	s_cbranch_vccz .LBB0_762
